# GEMM k-loops (on the version with the hoisted group-B hook test): each phase issues its fragment ds_reads right after the barrier, ahead of the DMA address / M0 setup
# baseline (speedup 1.0000x reference)
.LBB0_145:
	s_add_u32 s27, s50, 0x100
	s_addc_u32 s56, s51, 0
	s_mov_b32 s57, -2
	s_waitcnt lgkmcnt(0)
	ds_read_b128 v[128:131], v188
	ds_read_b128 v[132:135], v188 offset:1024
	ds_read_b128 v[136:139], v188 offset:2048
	ds_read_b128 v[140:143], v188 offset:3072
	ds_read_b128 v[144:147], v189
	ds_read_b128 v[148:151], v189 offset:1024
	ds_read_b128 v[176:179], v189 offset:2048
	ds_read_b128 v[180:183], v189 offset:3072
	s_add_u32 s50, s48, 0x100
	s_addc_u32 s51, s49, 0
	s_cmp_eq_u32 s57, 28
	s_cselect_b32 s55, s21, s51
	s_cselect_b32 s54, s20, s50
	s_cselect_b32 s53, s23, s56
	s_cselect_b32 s52, s22, s27
	v_lshl_add_u64 v[184:185], s[48:49], 0, v[170:171]
	s_add_i32 m0, s60, 0xc000
	ds_read_b128 v[194:197], v190
	ds_read_b128 v[198:201], v190 offset:1024
	ds_read_b128 v[202:205], v190 offset:2048
	ds_read_b128 v[206:209], v190 offset:3072
	ds_read_b128 v[210:213], v190 offset:4096
	ds_read_b128 v[214:217], v190 offset:5120
	ds_read_b128 v[218:221], v190 offset:6144
	ds_read_b128 v[222:225], v190 offset:7168
	global_load_lds_dwordx4 v[184:185], off
	v_lshl_add_u64 v[184:185], s[48:49], 0, v[172:173]
	s_add_i32 m0, s60, 0xe000
	s_nop 0
	global_load_lds_dwordx4 v[184:185], off
	s_waitcnt vmcnt(8)
	s_waitcnt lgkmcnt(0)
	s_waitcnt lgkmcnt(0)
	s_setprio 1
	s_barrier
	v_mfma_f32_16x16x32_bf16 v[120:123], v[128:131], v[194:197], 0
	v_mfma_f32_16x16x32_bf16 v[124:127], v[136:139], v[194:197], 0
	v_mfma_f32_16x16x32_bf16 v[108:111], v[128:131], v[202:205], 0
	v_mfma_f32_16x16x32_bf16 v[104:107], v[136:139], v[202:205], 0
	v_mfma_f32_16x16x32_bf16 v[92:95], v[128:131], v[210:213], 0
	v_mfma_f32_16x16x32_bf16 v[88:91], v[136:139], v[210:213], 0
	v_mfma_f32_16x16x32_bf16 v[76:79], v[128:131], v[218:221], 0
	v_mfma_f32_16x16x32_bf16 v[72:75], v[136:139], v[218:221], 0
	v_mfma_f32_16x16x32_bf16 v[120:123], v[132:135], v[198:201], v[120:123]
	v_mfma_f32_16x16x32_bf16 v[124:127], v[140:143], v[198:201], v[124:127]
	v_mfma_f32_16x16x32_bf16 v[108:111], v[132:135], v[206:209], v[108:111]
	v_mfma_f32_16x16x32_bf16 v[104:107], v[140:143], v[206:209], v[104:107]
	v_mfma_f32_16x16x32_bf16 v[92:95], v[132:135], v[214:217], v[92:95]
	v_mfma_f32_16x16x32_bf16 v[88:91], v[140:143], v[214:217], v[88:91]
	v_mfma_f32_16x16x32_bf16 v[76:79], v[132:135], v[222:225], v[76:79]
	v_mfma_f32_16x16x32_bf16 v[72:75], v[140:143], v[222:225], v[72:75]
	s_setprio 0
	s_setprio 1
	v_mfma_f32_16x16x32_bf16 v[112:115], v[144:147], v[194:197], 0
	v_mfma_f32_16x16x32_bf16 v[116:119], v[176:179], v[194:197], 0
	v_mfma_f32_16x16x32_bf16 v[100:103], v[144:147], v[202:205], 0
	v_mfma_f32_16x16x32_bf16 v[96:99], v[176:179], v[202:205], 0
	v_mfma_f32_16x16x32_bf16 v[84:87], v[144:147], v[210:213], 0
	v_mfma_f32_16x16x32_bf16 v[80:83], v[176:179], v[210:213], 0
	v_mfma_f32_16x16x32_bf16 v[68:71], v[144:147], v[218:221], 0
	v_mfma_f32_16x16x32_bf16 v[64:67], v[176:179], v[218:221], 0
	v_mfma_f32_16x16x32_bf16 v[112:115], v[148:151], v[198:201], v[112:115]
	v_mfma_f32_16x16x32_bf16 v[116:119], v[180:183], v[198:201], v[116:119]
	v_mfma_f32_16x16x32_bf16 v[100:103], v[148:151], v[206:209], v[100:103]
	v_mfma_f32_16x16x32_bf16 v[96:99], v[180:183], v[206:209], v[96:99]
	v_mfma_f32_16x16x32_bf16 v[84:87], v[148:151], v[214:217], v[84:87]
	v_mfma_f32_16x16x32_bf16 v[80:83], v[180:183], v[214:217], v[80:83]
	v_mfma_f32_16x16x32_bf16 v[68:71], v[148:151], v[222:225], v[68:71]
	v_mfma_f32_16x16x32_bf16 v[64:67], v[180:183], v[222:225], v[64:67]
	s_barrier
	s_setprio 0
	ds_read_b128 v[194:197], v190 offset:16384
	ds_read_b128 v[198:201], v190 offset:17408
	ds_read_b128 v[202:205], v190 offset:18432
	ds_read_b128 v[206:209], v190 offset:19456
	ds_read_b128 v[210:213], v190 offset:20480
	ds_read_b128 v[214:217], v190 offset:21504
	ds_read_b128 v[218:221], v190 offset:22528
	ds_read_b128 v[222:225], v190 offset:23552
	s_add_i32 s48, s71, s3
	s_mov_b32 m0, s48
	v_lshl_add_u64 v[184:185], s[52:53], 0, v[154:155]
	global_load_lds_dwordx4 v[184:185], off
	s_add_i32 m0, s48, 0x2000
	s_add_u32 s48, s52, 0x80000
	v_lshl_add_u64 v[226:227], s[52:53], 0, v[158:159]
	s_addc_u32 s49, s53, 0
	s_add_i32 s58, s72, s3
	global_load_lds_dwordx4 v[226:227], off
	v_lshl_add_u64 v[228:229], s[48:49], 0, v[154:155]
	s_mov_b32 m0, s58
	v_lshl_add_u64 v[230:231], s[54:55], 0, v[156:157]
	global_load_lds_dwordx4 v[228:229], off
	v_lshl_add_u64 v[228:229], s[48:49], 0, v[158:159]
	s_add_i32 m0, s58, 0x2000
	s_nop 0
	global_load_lds_dwordx4 v[228:229], off
	v_lshl_add_u64 v[228:229], s[54:55], 0, v[152:153]
	s_mov_b32 m0, s60
	s_nop 0
	global_load_lds_dwordx4 v[228:229], off
	s_mov_b32 m0, s61
	s_nop 0
	global_load_lds_dwordx4 v[230:231], off
	s_waitcnt vmcnt(8)
	s_waitcnt lgkmcnt(0)
	s_waitcnt lgkmcnt(0)
	s_setprio 1
	s_barrier
	v_mfma_f32_16x16x32_bf16 v[60:63], v[128:131], v[194:197], 0
	v_mfma_f32_16x16x32_bf16 v[56:59], v[136:139], v[194:197], 0
	v_mfma_f32_16x16x32_bf16 v[44:47], v[128:131], v[202:205], 0
	v_mfma_f32_16x16x32_bf16 v[40:43], v[136:139], v[202:205], 0
	v_mfma_f32_16x16x32_bf16 v[28:31], v[128:131], v[210:213], 0
	v_mfma_f32_16x16x32_bf16 v[24:27], v[136:139], v[210:213], 0
	v_mfma_f32_16x16x32_bf16 v[12:15], v[128:131], v[218:221], 0
	v_mfma_f32_16x16x32_bf16 v[8:11], v[136:139], v[218:221], 0
	v_mfma_f32_16x16x32_bf16 v[60:63], v[132:135], v[198:201], v[60:63]
	v_mfma_f32_16x16x32_bf16 v[56:59], v[140:143], v[198:201], v[56:59]
	v_mfma_f32_16x16x32_bf16 v[44:47], v[132:135], v[206:209], v[44:47]
	v_mfma_f32_16x16x32_bf16 v[40:43], v[140:143], v[206:209], v[40:43]
	v_mfma_f32_16x16x32_bf16 v[28:31], v[132:135], v[214:217], v[28:31]
	v_mfma_f32_16x16x32_bf16 v[24:27], v[140:143], v[214:217], v[24:27]
	v_mfma_f32_16x16x32_bf16 v[12:15], v[132:135], v[222:225], v[12:15]
	v_mfma_f32_16x16x32_bf16 v[8:11], v[140:143], v[222:225], v[8:11]
	s_setprio 0
	s_setprio 1
	v_mfma_f32_16x16x32_bf16 v[52:55], v[144:147], v[194:197], 0
	v_mfma_f32_16x16x32_bf16 v[48:51], v[176:179], v[194:197], 0
	v_mfma_f32_16x16x32_bf16 v[36:39], v[144:147], v[202:205], 0
	v_mfma_f32_16x16x32_bf16 v[32:35], v[176:179], v[202:205], 0
	v_mfma_f32_16x16x32_bf16 v[20:23], v[144:147], v[210:213], 0
	v_mfma_f32_16x16x32_bf16 v[16:19], v[176:179], v[210:213], 0
	v_mfma_f32_16x16x32_bf16 v[4:7], v[144:147], v[218:221], 0
	v_mfma_f32_16x16x32_bf16 v[0:3], v[176:179], v[218:221], 0
	v_mfma_f32_16x16x32_bf16 v[52:55], v[148:151], v[198:201], v[52:55]
	v_mfma_f32_16x16x32_bf16 v[48:51], v[180:183], v[198:201], v[48:51]
	v_mfma_f32_16x16x32_bf16 v[36:39], v[148:151], v[206:209], v[36:39]
	v_mfma_f32_16x16x32_bf16 v[32:35], v[180:183], v[206:209], v[32:35]
	v_mfma_f32_16x16x32_bf16 v[20:23], v[148:151], v[214:217], v[20:23]
	v_mfma_f32_16x16x32_bf16 v[16:19], v[180:183], v[214:217], v[16:19]
	v_mfma_f32_16x16x32_bf16 v[4:7], v[148:151], v[222:225], v[4:7]
	v_mfma_f32_16x16x32_bf16 v[0:3], v[180:183], v[222:225], v[0:3]
	s_barrier
	s_setprio 0
	s_branch .Lpeel_mid_p1
.LBB0_146:
	ds_read_b128 v[128:131], v188
	ds_read_b128 v[132:135], v188 offset:1024
	ds_read_b128 v[136:139], v188 offset:2048
	ds_read_b128 v[140:143], v188 offset:3072
	ds_read_b128 v[144:147], v189
	ds_read_b128 v[148:151], v189 offset:1024
	ds_read_b128 v[176:179], v189 offset:2048
	ds_read_b128 v[180:183], v189 offset:3072
	s_add_u32 s50, s48, 0x100
	s_addc_u32 s51, s49, 0
	s_cmp_eq_u32 s57, 28
	s_cselect_b32 s55, s21, s51
	s_cselect_b32 s54, s20, s50
	s_cselect_b32 s53, s23, s56
	s_cselect_b32 s52, s22, s27
	v_lshl_add_u64 v[184:185], s[48:49], 0, v[170:171]
	s_add_i32 m0, s60, 0xc000
	ds_read_b128 v[194:197], v190
	ds_read_b128 v[198:201], v190 offset:1024
	ds_read_b128 v[202:205], v190 offset:2048
	ds_read_b128 v[206:209], v190 offset:3072
	ds_read_b128 v[210:213], v190 offset:4096
	ds_read_b128 v[214:217], v190 offset:5120
	ds_read_b128 v[218:221], v190 offset:6144
	ds_read_b128 v[222:225], v190 offset:7168
	global_load_lds_dwordx4 v[184:185], off
	v_lshl_add_u64 v[184:185], s[48:49], 0, v[172:173]
	s_add_i32 m0, s60, 0xe000
	s_nop 0
	global_load_lds_dwordx4 v[184:185], off
	s_waitcnt vmcnt(8)
	s_waitcnt lgkmcnt(0)
	s_waitcnt lgkmcnt(0)
	s_setprio 1
	s_barrier
	v_mfma_f32_16x16x32_bf16 v[120:123], v[128:131], v[194:197], v[120:123]
	v_mfma_f32_16x16x32_bf16 v[124:127], v[136:139], v[194:197], v[124:127]
	v_mfma_f32_16x16x32_bf16 v[108:111], v[128:131], v[202:205], v[108:111]
	v_mfma_f32_16x16x32_bf16 v[104:107], v[136:139], v[202:205], v[104:107]
	v_mfma_f32_16x16x32_bf16 v[92:95], v[128:131], v[210:213], v[92:95]
	v_mfma_f32_16x16x32_bf16 v[88:91], v[136:139], v[210:213], v[88:91]
	v_mfma_f32_16x16x32_bf16 v[76:79], v[128:131], v[218:221], v[76:79]
	v_mfma_f32_16x16x32_bf16 v[72:75], v[136:139], v[218:221], v[72:75]
	v_mfma_f32_16x16x32_bf16 v[120:123], v[132:135], v[198:201], v[120:123]
	v_mfma_f32_16x16x32_bf16 v[124:127], v[140:143], v[198:201], v[124:127]
	v_mfma_f32_16x16x32_bf16 v[108:111], v[132:135], v[206:209], v[108:111]
	v_mfma_f32_16x16x32_bf16 v[104:107], v[140:143], v[206:209], v[104:107]
	v_mfma_f32_16x16x32_bf16 v[92:95], v[132:135], v[214:217], v[92:95]
	v_mfma_f32_16x16x32_bf16 v[88:91], v[140:143], v[214:217], v[88:91]
	v_mfma_f32_16x16x32_bf16 v[76:79], v[132:135], v[222:225], v[76:79]
	v_mfma_f32_16x16x32_bf16 v[72:75], v[140:143], v[222:225], v[72:75]
	s_setprio 0
	s_setprio 1
	v_mfma_f32_16x16x32_bf16 v[112:115], v[144:147], v[194:197], v[112:115]
	v_mfma_f32_16x16x32_bf16 v[116:119], v[176:179], v[194:197], v[116:119]
	v_mfma_f32_16x16x32_bf16 v[100:103], v[144:147], v[202:205], v[100:103]
	v_mfma_f32_16x16x32_bf16 v[96:99], v[176:179], v[202:205], v[96:99]
	v_mfma_f32_16x16x32_bf16 v[84:87], v[144:147], v[210:213], v[84:87]
	v_mfma_f32_16x16x32_bf16 v[80:83], v[176:179], v[210:213], v[80:83]
	v_mfma_f32_16x16x32_bf16 v[68:71], v[144:147], v[218:221], v[68:71]
	v_mfma_f32_16x16x32_bf16 v[64:67], v[176:179], v[218:221], v[64:67]
	v_mfma_f32_16x16x32_bf16 v[112:115], v[148:151], v[198:201], v[112:115]
	v_mfma_f32_16x16x32_bf16 v[116:119], v[180:183], v[198:201], v[116:119]
	v_mfma_f32_16x16x32_bf16 v[100:103], v[148:151], v[206:209], v[100:103]
	v_mfma_f32_16x16x32_bf16 v[96:99], v[180:183], v[206:209], v[96:99]
	v_mfma_f32_16x16x32_bf16 v[84:87], v[148:151], v[214:217], v[84:87]
	v_mfma_f32_16x16x32_bf16 v[80:83], v[180:183], v[214:217], v[80:83]
	v_mfma_f32_16x16x32_bf16 v[68:71], v[148:151], v[222:225], v[68:71]
	v_mfma_f32_16x16x32_bf16 v[64:67], v[180:183], v[222:225], v[64:67]
	s_barrier
	s_setprio 0
	ds_read_b128 v[194:197], v190 offset:16384
	ds_read_b128 v[198:201], v190 offset:17408
	ds_read_b128 v[202:205], v190 offset:18432
	ds_read_b128 v[206:209], v190 offset:19456
	ds_read_b128 v[210:213], v190 offset:20480
	ds_read_b128 v[214:217], v190 offset:21504
	ds_read_b128 v[218:221], v190 offset:22528
	ds_read_b128 v[222:225], v190 offset:23552
	s_add_i32 s48, s71, s3
	s_mov_b32 m0, s48
	v_lshl_add_u64 v[184:185], s[52:53], 0, v[154:155]
	global_load_lds_dwordx4 v[184:185], off
	s_add_i32 m0, s48, 0x2000
	s_add_u32 s48, s52, 0x80000
	v_lshl_add_u64 v[226:227], s[52:53], 0, v[158:159]
	s_addc_u32 s49, s53, 0
	s_add_i32 s58, s72, s3
	global_load_lds_dwordx4 v[226:227], off
	v_lshl_add_u64 v[228:229], s[48:49], 0, v[154:155]
	s_mov_b32 m0, s58
	v_lshl_add_u64 v[230:231], s[54:55], 0, v[156:157]
	global_load_lds_dwordx4 v[228:229], off
	v_lshl_add_u64 v[228:229], s[48:49], 0, v[158:159]
	s_add_i32 m0, s58, 0x2000
	s_nop 0
	global_load_lds_dwordx4 v[228:229], off
	v_lshl_add_u64 v[228:229], s[54:55], 0, v[152:153]
	s_mov_b32 m0, s60
	s_nop 0
	global_load_lds_dwordx4 v[228:229], off
	s_mov_b32 m0, s61
	s_nop 0
	global_load_lds_dwordx4 v[230:231], off
	s_waitcnt vmcnt(8)
	s_waitcnt lgkmcnt(0)
	s_waitcnt lgkmcnt(0)
	s_setprio 1
	s_barrier
	v_mfma_f32_16x16x32_bf16 v[60:63], v[128:131], v[194:197], v[60:63]
	v_mfma_f32_16x16x32_bf16 v[56:59], v[136:139], v[194:197], v[56:59]
	v_mfma_f32_16x16x32_bf16 v[44:47], v[128:131], v[202:205], v[44:47]
	v_mfma_f32_16x16x32_bf16 v[40:43], v[136:139], v[202:205], v[40:43]
	v_mfma_f32_16x16x32_bf16 v[28:31], v[128:131], v[210:213], v[28:31]
	v_mfma_f32_16x16x32_bf16 v[24:27], v[136:139], v[210:213], v[24:27]
	v_mfma_f32_16x16x32_bf16 v[12:15], v[128:131], v[218:221], v[12:15]
	v_mfma_f32_16x16x32_bf16 v[8:11], v[136:139], v[218:221], v[8:11]
	v_mfma_f32_16x16x32_bf16 v[60:63], v[132:135], v[198:201], v[60:63]
	v_mfma_f32_16x16x32_bf16 v[56:59], v[140:143], v[198:201], v[56:59]
	v_mfma_f32_16x16x32_bf16 v[44:47], v[132:135], v[206:209], v[44:47]
	v_mfma_f32_16x16x32_bf16 v[40:43], v[140:143], v[206:209], v[40:43]
	v_mfma_f32_16x16x32_bf16 v[28:31], v[132:135], v[214:217], v[28:31]
	v_mfma_f32_16x16x32_bf16 v[24:27], v[140:143], v[214:217], v[24:27]
	v_mfma_f32_16x16x32_bf16 v[12:15], v[132:135], v[222:225], v[12:15]
	v_mfma_f32_16x16x32_bf16 v[8:11], v[140:143], v[222:225], v[8:11]
	s_setprio 0
	s_setprio 1
	v_mfma_f32_16x16x32_bf16 v[52:55], v[144:147], v[194:197], v[52:55]
	v_mfma_f32_16x16x32_bf16 v[48:51], v[176:179], v[194:197], v[48:51]
	v_mfma_f32_16x16x32_bf16 v[36:39], v[144:147], v[202:205], v[36:39]
	v_mfma_f32_16x16x32_bf16 v[32:35], v[176:179], v[202:205], v[32:35]
	v_mfma_f32_16x16x32_bf16 v[20:23], v[144:147], v[210:213], v[20:23]
	v_mfma_f32_16x16x32_bf16 v[16:19], v[176:179], v[210:213], v[16:19]
	v_mfma_f32_16x16x32_bf16 v[4:7], v[144:147], v[218:221], v[4:7]
	v_mfma_f32_16x16x32_bf16 v[0:3], v[176:179], v[218:221], v[0:3]
	v_mfma_f32_16x16x32_bf16 v[52:55], v[148:151], v[198:201], v[52:55]
	v_mfma_f32_16x16x32_bf16 v[48:51], v[180:183], v[198:201], v[48:51]
	v_mfma_f32_16x16x32_bf16 v[36:39], v[148:151], v[206:209], v[36:39]
	v_mfma_f32_16x16x32_bf16 v[32:35], v[180:183], v[206:209], v[32:35]
	v_mfma_f32_16x16x32_bf16 v[20:23], v[148:151], v[214:217], v[20:23]
	v_mfma_f32_16x16x32_bf16 v[16:19], v[180:183], v[214:217], v[16:19]
	v_mfma_f32_16x16x32_bf16 v[4:7], v[148:151], v[222:225], v[4:7]
	v_mfma_f32_16x16x32_bf16 v[0:3], v[180:183], v[222:225], v[0:3]
	s_barrier
	s_setprio 0
.Lpeel_mid_p1:
	s_add_i32 s58, 0, 0x18000
	s_add_i32 s59, 0, 0x1c000
	v_add_u32_e32 v140, s58, v186
	v_add_u32_e32 v160, s59, v186
	ds_read_b128 v[128:131], v140
	ds_read_b128 v[132:135], v140 offset:1024
	ds_read_b128 v[136:139], v140 offset:2048
	ds_read_b128 v[140:143], v140 offset:3072
	ds_read_b128 v[144:147], v160
	ds_read_b128 v[148:151], v160 offset:1024
	ds_read_b128 v[176:179], v160 offset:2048
	ds_read_b128 v[180:183], v160 offset:3072
	s_add_u32 s48, s54, 0xa0000
	s_addc_u32 s49, s55, 0
	s_mov_b32 m0, s62
	v_lshl_add_u64 v[232:233], s[48:49], 0, v[152:153]
	ds_read_b128 v[194:197], v190 offset:32768
	ds_read_b128 v[198:201], v190 offset:33792
	ds_read_b128 v[202:205], v190 offset:34816
	ds_read_b128 v[206:209], v190 offset:35840
	ds_read_b128 v[210:213], v190 offset:36864
	ds_read_b128 v[214:217], v190 offset:37888
	ds_read_b128 v[218:221], v190 offset:38912
	ds_read_b128 v[222:225], v190 offset:39936
	global_load_lds_dwordx4 v[232:233], off
	v_lshl_add_u64 v[232:233], s[48:49], 0, v[156:157]
	s_mov_b32 m0, s63
	s_nop 0
	global_load_lds_dwordx4 v[232:233], off
	s_waitcnt vmcnt(8)
	s_waitcnt lgkmcnt(0)
	s_waitcnt lgkmcnt(0)
	s_setprio 1
	s_barrier
	v_mfma_f32_16x16x32_bf16 v[120:123], v[128:131], v[194:197], v[120:123]
	v_mfma_f32_16x16x32_bf16 v[124:127], v[136:139], v[194:197], v[124:127]
	v_mfma_f32_16x16x32_bf16 v[108:111], v[128:131], v[202:205], v[108:111]
	v_mfma_f32_16x16x32_bf16 v[104:107], v[136:139], v[202:205], v[104:107]
	v_mfma_f32_16x16x32_bf16 v[92:95], v[128:131], v[210:213], v[92:95]
	v_mfma_f32_16x16x32_bf16 v[88:91], v[136:139], v[210:213], v[88:91]
	v_mfma_f32_16x16x32_bf16 v[76:79], v[128:131], v[218:221], v[76:79]
	v_mfma_f32_16x16x32_bf16 v[72:75], v[136:139], v[218:221], v[72:75]
	v_mfma_f32_16x16x32_bf16 v[120:123], v[132:135], v[198:201], v[120:123]
	v_mfma_f32_16x16x32_bf16 v[124:127], v[140:143], v[198:201], v[124:127]
	v_mfma_f32_16x16x32_bf16 v[108:111], v[132:135], v[206:209], v[108:111]
	v_mfma_f32_16x16x32_bf16 v[104:107], v[140:143], v[206:209], v[104:107]
	v_mfma_f32_16x16x32_bf16 v[92:95], v[132:135], v[214:217], v[92:95]
	v_mfma_f32_16x16x32_bf16 v[88:91], v[140:143], v[214:217], v[88:91]
	v_mfma_f32_16x16x32_bf16 v[76:79], v[132:135], v[222:225], v[76:79]
	v_mfma_f32_16x16x32_bf16 v[72:75], v[140:143], v[222:225], v[72:75]
	s_setprio 0
	s_setprio 1
	v_mfma_f32_16x16x32_bf16 v[112:115], v[144:147], v[194:197], v[112:115]
	v_mfma_f32_16x16x32_bf16 v[116:119], v[176:179], v[194:197], v[116:119]
	v_mfma_f32_16x16x32_bf16 v[100:103], v[144:147], v[202:205], v[100:103]
	v_mfma_f32_16x16x32_bf16 v[96:99], v[176:179], v[202:205], v[96:99]
	v_mfma_f32_16x16x32_bf16 v[84:87], v[144:147], v[210:213], v[84:87]
	v_mfma_f32_16x16x32_bf16 v[80:83], v[176:179], v[210:213], v[80:83]
	v_mfma_f32_16x16x32_bf16 v[68:71], v[144:147], v[218:221], v[68:71]
	v_mfma_f32_16x16x32_bf16 v[64:67], v[176:179], v[218:221], v[64:67]
	v_mfma_f32_16x16x32_bf16 v[112:115], v[148:151], v[198:201], v[112:115]
	v_mfma_f32_16x16x32_bf16 v[116:119], v[180:183], v[198:201], v[116:119]
	v_mfma_f32_16x16x32_bf16 v[100:103], v[148:151], v[206:209], v[100:103]
	v_mfma_f32_16x16x32_bf16 v[96:99], v[180:183], v[206:209], v[96:99]
	v_mfma_f32_16x16x32_bf16 v[84:87], v[148:151], v[214:217], v[84:87]
	v_mfma_f32_16x16x32_bf16 v[80:83], v[180:183], v[214:217], v[80:83]
	v_mfma_f32_16x16x32_bf16 v[68:71], v[148:151], v[222:225], v[68:71]
	v_mfma_f32_16x16x32_bf16 v[64:67], v[180:183], v[222:225], v[64:67]
	s_barrier
	s_setprio 0
	ds_read_b128 v[194:197], v190 offset:49152
	ds_read_b128 v[198:201], v190 offset:50176
	ds_read_b128 v[202:205], v190 offset:51200
	ds_read_b128 v[206:209], v190 offset:52224
	ds_read_b128 v[210:213], v190 offset:53248
	ds_read_b128 v[214:217], v190 offset:54272
	ds_read_b128 v[218:221], v190 offset:55296
	ds_read_b128 v[222:225], v190 offset:56320
	s_add_i32 s48, s58, s3
	s_mov_b32 m0, s48
	v_lshl_add_u64 v[184:185], v[184:185], 0, s[14:15]
	global_load_lds_dwordx4 v[184:185], off
	s_add_i32 m0, s48, 0x2000
	s_add_u32 s48, s52, 0x80080
	v_lshl_add_u64 v[184:185], v[226:227], 0, s[14:15]
	s_addc_u32 s49, s53, 0
	s_add_i32 s52, s59, s3
	global_load_lds_dwordx4 v[184:185], off
	v_lshl_add_u64 v[184:185], s[48:49], 0, v[154:155]
	s_mov_b32 m0, s52
	s_nop 0
	global_load_lds_dwordx4 v[184:185], off
	v_lshl_add_u64 v[184:185], s[48:49], 0, v[158:159]
	s_add_i32 m0, s52, 0x2000
	s_nop 0
	global_load_lds_dwordx4 v[184:185], off
	v_lshl_add_u64 v[184:185], v[228:229], 0, s[14:15]
	s_mov_b32 m0, s66
	s_nop 0
	global_load_lds_dwordx4 v[184:185], off
	v_lshl_add_u64 v[184:185], v[230:231], 0, s[14:15]
	s_mov_b32 m0, s67
	s_nop 0
	global_load_lds_dwordx4 v[184:185], off
	s_waitcnt vmcnt(8)
	s_waitcnt lgkmcnt(0)
	s_waitcnt lgkmcnt(0)
	s_setprio 1
	s_barrier
	v_mfma_f32_16x16x32_bf16 v[60:63], v[128:131], v[194:197], v[60:63]
	v_mfma_f32_16x16x32_bf16 v[56:59], v[136:139], v[194:197], v[56:59]
	v_mfma_f32_16x16x32_bf16 v[44:47], v[128:131], v[202:205], v[44:47]
	v_mfma_f32_16x16x32_bf16 v[40:43], v[136:139], v[202:205], v[40:43]
	v_mfma_f32_16x16x32_bf16 v[28:31], v[128:131], v[210:213], v[28:31]
	v_mfma_f32_16x16x32_bf16 v[24:27], v[136:139], v[210:213], v[24:27]
	v_mfma_f32_16x16x32_bf16 v[12:15], v[128:131], v[218:221], v[12:15]
	v_mfma_f32_16x16x32_bf16 v[8:11], v[136:139], v[218:221], v[8:11]
	v_mfma_f32_16x16x32_bf16 v[60:63], v[132:135], v[198:201], v[60:63]
	v_mfma_f32_16x16x32_bf16 v[56:59], v[140:143], v[198:201], v[56:59]
	v_mfma_f32_16x16x32_bf16 v[44:47], v[132:135], v[206:209], v[44:47]
	v_mfma_f32_16x16x32_bf16 v[40:43], v[140:143], v[206:209], v[40:43]
	v_mfma_f32_16x16x32_bf16 v[28:31], v[132:135], v[214:217], v[28:31]
	v_mfma_f32_16x16x32_bf16 v[24:27], v[140:143], v[214:217], v[24:27]
	v_mfma_f32_16x16x32_bf16 v[12:15], v[132:135], v[222:225], v[12:15]
	v_mfma_f32_16x16x32_bf16 v[8:11], v[140:143], v[222:225], v[8:11]
	s_setprio 0
	s_setprio 1
	v_mfma_f32_16x16x32_bf16 v[52:55], v[144:147], v[194:197], v[52:55]
	v_mfma_f32_16x16x32_bf16 v[48:51], v[176:179], v[194:197], v[48:51]
	v_mfma_f32_16x16x32_bf16 v[36:39], v[144:147], v[202:205], v[36:39]
	v_mfma_f32_16x16x32_bf16 v[32:35], v[176:179], v[202:205], v[32:35]
	s_add_i32 s57, s57, 2
	v_mfma_f32_16x16x32_bf16 v[20:23], v[144:147], v[210:213], v[20:23]
	s_add_u32 s27, s27, 0x100
	v_mfma_f32_16x16x32_bf16 v[16:19], v[176:179], v[210:213], v[16:19]
	s_addc_u32 s56, s56, 0
	v_mfma_f32_16x16x32_bf16 v[4:7], v[144:147], v[218:221], v[4:7]
	s_cmp_gt_u32 s57, 29
	v_mfma_f32_16x16x32_bf16 v[0:3], v[176:179], v[218:221], v[0:3]
	s_mov_b64 s[48:49], s[50:51]
	v_mfma_f32_16x16x32_bf16 v[52:55], v[148:151], v[198:201], v[52:55]
	v_mfma_f32_16x16x32_bf16 v[48:51], v[180:183], v[198:201], v[48:51]
	v_mfma_f32_16x16x32_bf16 v[36:39], v[148:151], v[206:209], v[36:39]
	v_mfma_f32_16x16x32_bf16 v[32:35], v[180:183], v[206:209], v[32:35]
	v_mfma_f32_16x16x32_bf16 v[20:23], v[148:151], v[214:217], v[20:23]
	v_mfma_f32_16x16x32_bf16 v[16:19], v[180:183], v[214:217], v[16:19]
	v_mfma_f32_16x16x32_bf16 v[4:7], v[148:151], v[222:225], v[4:7]
	v_mfma_f32_16x16x32_bf16 v[0:3], v[180:183], v[222:225], v[0:3]
	s_barrier
	s_setprio 0
	s_cbranch_scc0 .LBB0_146
	s_and_b64 vcc, exec, s[18:19]
	s_cbranch_vccz .LBB0_149
	s_barrier

.LBB0_250:
	ds_read_b128 v[148:151], v142
	ds_read_b128 v[152:155], v142 offset:1024
	ds_read_b128 v[156:159], v142 offset:2048
	ds_read_b128 v[160:163], v142 offset:3072
	ds_read_b128 v[164:167], v143
	ds_read_b128 v[168:171], v143 offset:1024
	ds_read_b128 v[176:179], v143 offset:2048
	ds_read_b128 v[180:183], v143 offset:3072
	s_add_i32 s20, s18, 0xf4f60080
	s_cmp_lg_u32 s52, 28
	s_cselect_b32 s20, s20, 0
	s_add_u32 s22, s2, s20
	s_addc_u32 s23, s3, 0
	s_add_u32 s20, s12, s20
	s_addc_u32 s21, s13, 0
	s_mov_b32 m0, s53
	v_lshl_add_u64 v[172:173], v[138:139], 0, s[18:19]
	ds_read_b128 v[188:191], v144
	ds_read_b128 v[192:195], v144 offset:1024
	ds_read_b128 v[196:199], v144 offset:2048
	ds_read_b128 v[200:203], v144 offset:3072
	ds_read_b128 v[204:207], v144 offset:4096
	ds_read_b128 v[208:211], v144 offset:5120
	ds_read_b128 v[212:215], v144 offset:6144
	ds_read_b128 v[216:219], v144 offset:7168
	global_load_lds_dwordx4 v[172:173], off
	v_lshl_add_u64 v[172:173], v[140:141], 0, s[18:19]
	s_mov_b32 m0, s54
	s_nop 0
	global_load_lds_dwordx4 v[172:173], off
	s_waitcnt vmcnt(8)
	s_waitcnt lgkmcnt(0)
	s_waitcnt lgkmcnt(0)
	s_setprio 1
	s_barrier
	v_mfma_f32_16x16x32_bf16 v[124:127], v[148:151], v[188:191], v[124:127]
	v_mfma_f32_16x16x32_bf16 v[120:123], v[156:159], v[188:191], v[120:123]
	v_mfma_f32_16x16x32_bf16 v[116:119], v[148:151], v[196:199], v[116:119]
	v_mfma_f32_16x16x32_bf16 v[112:115], v[156:159], v[196:199], v[112:115]
	v_mfma_f32_16x16x32_bf16 v[100:103], v[148:151], v[204:207], v[100:103]
	v_mfma_f32_16x16x32_bf16 v[96:99], v[156:159], v[204:207], v[96:99]
	v_mfma_f32_16x16x32_bf16 v[84:87], v[148:151], v[212:215], v[84:87]
	v_mfma_f32_16x16x32_bf16 v[80:83], v[156:159], v[212:215], v[80:83]
	v_mfma_f32_16x16x32_bf16 v[124:127], v[152:155], v[192:195], v[124:127]
	v_mfma_f32_16x16x32_bf16 v[120:123], v[160:163], v[192:195], v[120:123]
	v_mfma_f32_16x16x32_bf16 v[116:119], v[152:155], v[200:203], v[116:119]
	v_mfma_f32_16x16x32_bf16 v[112:115], v[160:163], v[200:203], v[112:115]
	v_mfma_f32_16x16x32_bf16 v[100:103], v[152:155], v[208:211], v[100:103]
	v_mfma_f32_16x16x32_bf16 v[96:99], v[160:163], v[208:211], v[96:99]
	v_mfma_f32_16x16x32_bf16 v[84:87], v[152:155], v[216:219], v[84:87]
	v_mfma_f32_16x16x32_bf16 v[80:83], v[160:163], v[216:219], v[80:83]
	s_setprio 0
	s_setprio 1
	v_mfma_f32_16x16x32_bf16 v[108:111], v[164:167], v[188:191], v[108:111]
	v_mfma_f32_16x16x32_bf16 v[104:107], v[176:179], v[188:191], v[104:107]
	v_mfma_f32_16x16x32_bf16 v[92:95], v[164:167], v[196:199], v[92:95]
	v_mfma_f32_16x16x32_bf16 v[88:91], v[176:179], v[196:199], v[88:91]
	v_mfma_f32_16x16x32_bf16 v[76:79], v[164:167], v[204:207], v[76:79]
	v_mfma_f32_16x16x32_bf16 v[72:75], v[176:179], v[204:207], v[72:75]
	v_mfma_f32_16x16x32_bf16 v[68:71], v[164:167], v[212:215], v[68:71]
	v_mfma_f32_16x16x32_bf16 v[64:67], v[176:179], v[212:215], v[64:67]
	v_mfma_f32_16x16x32_bf16 v[108:111], v[168:171], v[192:195], v[108:111]
	v_mfma_f32_16x16x32_bf16 v[104:107], v[180:183], v[192:195], v[104:107]
	v_mfma_f32_16x16x32_bf16 v[92:95], v[168:171], v[200:203], v[92:95]
	v_mfma_f32_16x16x32_bf16 v[88:91], v[180:183], v[200:203], v[88:91]
	v_mfma_f32_16x16x32_bf16 v[76:79], v[168:171], v[208:211], v[76:79]
	v_mfma_f32_16x16x32_bf16 v[72:75], v[180:183], v[208:211], v[72:75]
	v_mfma_f32_16x16x32_bf16 v[68:71], v[168:171], v[216:219], v[68:71]
	v_mfma_f32_16x16x32_bf16 v[64:67], v[180:183], v[216:219], v[64:67]
	s_barrier
	s_setprio 0
	ds_read_b128 v[188:191], v144 offset:16384
	ds_read_b128 v[192:195], v144 offset:17408
	ds_read_b128 v[196:199], v144 offset:18432
	ds_read_b128 v[200:203], v144 offset:19456
	ds_read_b128 v[204:207], v144 offset:20480
	ds_read_b128 v[208:211], v144 offset:21504
	ds_read_b128 v[212:215], v144 offset:22528
	ds_read_b128 v[216:219], v144 offset:23552
	s_mov_b32 m0, s55
	v_lshl_add_u64 v[172:173], s[20:21], 0, v[132:133]
	s_add_u32 s64, s20, 0x80000
	global_load_lds_dwordx4 v[172:173], off
	v_lshl_add_u64 v[184:185], s[20:21], 0, v[128:129]
	s_mov_b32 m0, s56
	s_addc_u32 s65, s21, 0
	global_load_lds_dwordx4 v[184:185], off
	v_lshl_add_u64 v[220:221], s[64:65], 0, v[132:133]
	s_mov_b32 m0, s57
	v_lshl_add_u64 v[222:223], s[22:23], 0, v[130:131]
	global_load_lds_dwordx4 v[220:221], off
	v_lshl_add_u64 v[220:221], s[64:65], 0, v[128:129]
	s_mov_b32 m0, s58
	s_nop 0
	global_load_lds_dwordx4 v[220:221], off
	v_lshl_add_u64 v[220:221], s[22:23], 0, v[134:135]
	s_mov_b32 m0, s1
	s_nop 0
	global_load_lds_dwordx4 v[220:221], off
	s_mov_b32 m0, s26
	s_nop 0
	global_load_lds_dwordx4 v[222:223], off
	s_waitcnt vmcnt(8)
	s_waitcnt lgkmcnt(0)
	s_waitcnt lgkmcnt(0)
	s_setprio 1
	s_barrier
	v_mfma_f32_16x16x32_bf16 v[60:63], v[148:151], v[188:191], v[60:63]
	v_mfma_f32_16x16x32_bf16 v[56:59], v[156:159], v[188:191], v[56:59]
	v_mfma_f32_16x16x32_bf16 v[52:55], v[148:151], v[196:199], v[52:55]
	v_mfma_f32_16x16x32_bf16 v[48:51], v[156:159], v[196:199], v[48:51]
	v_mfma_f32_16x16x32_bf16 v[36:39], v[148:151], v[204:207], v[36:39]
	v_mfma_f32_16x16x32_bf16 v[32:35], v[156:159], v[204:207], v[32:35]
	v_mfma_f32_16x16x32_bf16 v[20:23], v[148:151], v[212:215], v[20:23]
	v_mfma_f32_16x16x32_bf16 v[16:19], v[156:159], v[212:215], v[16:19]
	v_mfma_f32_16x16x32_bf16 v[60:63], v[152:155], v[192:195], v[60:63]
	v_mfma_f32_16x16x32_bf16 v[56:59], v[160:163], v[192:195], v[56:59]
	v_mfma_f32_16x16x32_bf16 v[52:55], v[152:155], v[200:203], v[52:55]
	v_mfma_f32_16x16x32_bf16 v[48:51], v[160:163], v[200:203], v[48:51]
	v_mfma_f32_16x16x32_bf16 v[36:39], v[152:155], v[208:211], v[36:39]
	v_mfma_f32_16x16x32_bf16 v[32:35], v[160:163], v[208:211], v[32:35]
	v_mfma_f32_16x16x32_bf16 v[20:23], v[152:155], v[216:219], v[20:23]
	v_mfma_f32_16x16x32_bf16 v[16:19], v[160:163], v[216:219], v[16:19]
	s_setprio 0
	s_setprio 1
	v_mfma_f32_16x16x32_bf16 v[44:47], v[164:167], v[188:191], v[44:47]
	v_mfma_f32_16x16x32_bf16 v[40:43], v[176:179], v[188:191], v[40:43]
	v_mfma_f32_16x16x32_bf16 v[28:31], v[164:167], v[196:199], v[28:31]
	v_mfma_f32_16x16x32_bf16 v[24:27], v[176:179], v[196:199], v[24:27]
	v_mfma_f32_16x16x32_bf16 v[12:15], v[164:167], v[204:207], v[12:15]
	v_mfma_f32_16x16x32_bf16 v[8:11], v[176:179], v[204:207], v[8:11]
	v_mfma_f32_16x16x32_bf16 v[4:7], v[164:167], v[212:215], v[4:7]
	v_mfma_f32_16x16x32_bf16 v[0:3], v[176:179], v[212:215], v[0:3]
	v_mfma_f32_16x16x32_bf16 v[44:47], v[168:171], v[192:195], v[44:47]
	v_mfma_f32_16x16x32_bf16 v[40:43], v[180:183], v[192:195], v[40:43]
	v_mfma_f32_16x16x32_bf16 v[28:31], v[168:171], v[200:203], v[28:31]
	v_mfma_f32_16x16x32_bf16 v[24:27], v[180:183], v[200:203], v[24:27]
	v_mfma_f32_16x16x32_bf16 v[12:15], v[168:171], v[208:211], v[12:15]
	v_mfma_f32_16x16x32_bf16 v[8:11], v[180:183], v[208:211], v[8:11]
	v_mfma_f32_16x16x32_bf16 v[4:7], v[168:171], v[216:219], v[4:7]
	v_mfma_f32_16x16x32_bf16 v[0:3], v[180:183], v[216:219], v[0:3]
	s_barrier
	s_setprio 0
	ds_read_b128 v[148:151], v145
	ds_read_b128 v[152:155], v145 offset:1024
	ds_read_b128 v[156:159], v145 offset:2048
	ds_read_b128 v[160:163], v145 offset:3072
	ds_read_b128 v[164:167], v146
	ds_read_b128 v[168:171], v146 offset:1024
	ds_read_b128 v[176:179], v146 offset:2048
	ds_read_b128 v[180:183], v146 offset:3072
	s_add_u32 s22, s22, 0xa0000
	s_addc_u32 s23, s23, 0
	s_mov_b32 m0, s27
	v_lshl_add_u64 v[224:225], s[22:23], 0, v[134:135]
	ds_read_b128 v[188:191], v144 offset:32768
	ds_read_b128 v[192:195], v144 offset:33792
	ds_read_b128 v[196:199], v144 offset:34816
	ds_read_b128 v[200:203], v144 offset:35840
	ds_read_b128 v[204:207], v144 offset:36864
	ds_read_b128 v[208:211], v144 offset:37888
	ds_read_b128 v[212:215], v144 offset:38912
	ds_read_b128 v[216:219], v144 offset:39936
	global_load_lds_dwordx4 v[224:225], off
	v_lshl_add_u64 v[224:225], s[22:23], 0, v[130:131]
	s_mov_b32 m0, s48
	s_nop 0
	global_load_lds_dwordx4 v[224:225], off
	s_waitcnt vmcnt(8)
	s_waitcnt lgkmcnt(0)
	s_waitcnt lgkmcnt(0)
	s_setprio 1
	s_barrier
	v_mfma_f32_16x16x32_bf16 v[124:127], v[148:151], v[188:191], v[124:127]
	v_mfma_f32_16x16x32_bf16 v[120:123], v[156:159], v[188:191], v[120:123]
	v_mfma_f32_16x16x32_bf16 v[116:119], v[148:151], v[196:199], v[116:119]
	v_mfma_f32_16x16x32_bf16 v[112:115], v[156:159], v[196:199], v[112:115]
	v_mfma_f32_16x16x32_bf16 v[100:103], v[148:151], v[204:207], v[100:103]
	v_mfma_f32_16x16x32_bf16 v[96:99], v[156:159], v[204:207], v[96:99]
	v_mfma_f32_16x16x32_bf16 v[84:87], v[148:151], v[212:215], v[84:87]
	v_mfma_f32_16x16x32_bf16 v[80:83], v[156:159], v[212:215], v[80:83]
	v_mfma_f32_16x16x32_bf16 v[124:127], v[152:155], v[192:195], v[124:127]
	v_mfma_f32_16x16x32_bf16 v[120:123], v[160:163], v[192:195], v[120:123]
	v_mfma_f32_16x16x32_bf16 v[116:119], v[152:155], v[200:203], v[116:119]
	v_mfma_f32_16x16x32_bf16 v[112:115], v[160:163], v[200:203], v[112:115]
	v_mfma_f32_16x16x32_bf16 v[100:103], v[152:155], v[208:211], v[100:103]
	v_mfma_f32_16x16x32_bf16 v[96:99], v[160:163], v[208:211], v[96:99]
	v_mfma_f32_16x16x32_bf16 v[84:87], v[152:155], v[216:219], v[84:87]
	v_mfma_f32_16x16x32_bf16 v[80:83], v[160:163], v[216:219], v[80:83]
	s_setprio 0
	s_setprio 1
	v_mfma_f32_16x16x32_bf16 v[108:111], v[164:167], v[188:191], v[108:111]
	v_mfma_f32_16x16x32_bf16 v[104:107], v[176:179], v[188:191], v[104:107]
	v_mfma_f32_16x16x32_bf16 v[92:95], v[164:167], v[196:199], v[92:95]
	v_mfma_f32_16x16x32_bf16 v[88:91], v[176:179], v[196:199], v[88:91]
	v_mfma_f32_16x16x32_bf16 v[76:79], v[164:167], v[204:207], v[76:79]
	v_mfma_f32_16x16x32_bf16 v[72:75], v[176:179], v[204:207], v[72:75]
	v_mfma_f32_16x16x32_bf16 v[68:71], v[164:167], v[212:215], v[68:71]
	v_mfma_f32_16x16x32_bf16 v[64:67], v[176:179], v[212:215], v[64:67]
	v_mfma_f32_16x16x32_bf16 v[108:111], v[168:171], v[192:195], v[108:111]
	v_mfma_f32_16x16x32_bf16 v[104:107], v[180:183], v[192:195], v[104:107]
	v_mfma_f32_16x16x32_bf16 v[92:95], v[168:171], v[200:203], v[92:95]
	v_mfma_f32_16x16x32_bf16 v[88:91], v[180:183], v[200:203], v[88:91]
	v_mfma_f32_16x16x32_bf16 v[76:79], v[168:171], v[208:211], v[76:79]
	v_mfma_f32_16x16x32_bf16 v[72:75], v[180:183], v[208:211], v[72:75]
	v_mfma_f32_16x16x32_bf16 v[68:71], v[168:171], v[216:219], v[68:71]
	v_mfma_f32_16x16x32_bf16 v[64:67], v[180:183], v[216:219], v[64:67]
	s_barrier
	s_setprio 0
	ds_read_b128 v[188:191], v144 offset:49152
	ds_read_b128 v[192:195], v144 offset:50176
	ds_read_b128 v[196:199], v144 offset:51200
	ds_read_b128 v[200:203], v144 offset:52224
	ds_read_b128 v[204:207], v144 offset:53248
	ds_read_b128 v[208:211], v144 offset:54272
	ds_read_b128 v[212:215], v144 offset:55296
	ds_read_b128 v[216:219], v144 offset:56320
	s_mov_b32 m0, s59
	v_lshl_add_u64 v[172:173], v[172:173], 0, s[14:15]
	s_add_u32 s20, s20, 0x80080
	global_load_lds_dwordx4 v[172:173], off
	v_lshl_add_u64 v[172:173], v[184:185], 0, s[14:15]
	s_mov_b32 m0, s60
	s_addc_u32 s21, s21, 0
	global_load_lds_dwordx4 v[172:173], off
	v_lshl_add_u64 v[172:173], s[20:21], 0, v[132:133]
	s_mov_b32 m0, s61
	s_nop 0
	global_load_lds_dwordx4 v[172:173], off
	v_lshl_add_u64 v[172:173], s[20:21], 0, v[128:129]
	s_mov_b32 m0, s62
	s_nop 0
	global_load_lds_dwordx4 v[172:173], off
	v_lshl_add_u64 v[172:173], v[220:221], 0, s[14:15]
	s_mov_b32 m0, s50
	s_nop 0
	global_load_lds_dwordx4 v[172:173], off
	v_lshl_add_u64 v[172:173], v[222:223], 0, s[14:15]
	s_mov_b32 m0, s51
	s_nop 0
	global_load_lds_dwordx4 v[172:173], off
	s_waitcnt vmcnt(8)
	s_waitcnt lgkmcnt(0)
	s_waitcnt lgkmcnt(0)
	s_setprio 1
	s_barrier
	v_mfma_f32_16x16x32_bf16 v[60:63], v[148:151], v[188:191], v[60:63]
	v_mfma_f32_16x16x32_bf16 v[56:59], v[156:159], v[188:191], v[56:59]
	v_mfma_f32_16x16x32_bf16 v[52:55], v[148:151], v[196:199], v[52:55]
	v_mfma_f32_16x16x32_bf16 v[48:51], v[156:159], v[196:199], v[48:51]
	v_mfma_f32_16x16x32_bf16 v[36:39], v[148:151], v[204:207], v[36:39]
	v_mfma_f32_16x16x32_bf16 v[32:35], v[156:159], v[204:207], v[32:35]
	v_mfma_f32_16x16x32_bf16 v[20:23], v[148:151], v[212:215], v[20:23]
	v_mfma_f32_16x16x32_bf16 v[16:19], v[156:159], v[212:215], v[16:19]
	v_mfma_f32_16x16x32_bf16 v[60:63], v[152:155], v[192:195], v[60:63]
	v_mfma_f32_16x16x32_bf16 v[56:59], v[160:163], v[192:195], v[56:59]
	v_mfma_f32_16x16x32_bf16 v[52:55], v[152:155], v[200:203], v[52:55]
	v_mfma_f32_16x16x32_bf16 v[48:51], v[160:163], v[200:203], v[48:51]
	v_mfma_f32_16x16x32_bf16 v[36:39], v[152:155], v[208:211], v[36:39]
	v_mfma_f32_16x16x32_bf16 v[32:35], v[160:163], v[208:211], v[32:35]
	v_mfma_f32_16x16x32_bf16 v[20:23], v[152:155], v[216:219], v[20:23]
	v_mfma_f32_16x16x32_bf16 v[16:19], v[160:163], v[216:219], v[16:19]
	s_setprio 0
	s_setprio 1
	v_mfma_f32_16x16x32_bf16 v[44:47], v[164:167], v[188:191], v[44:47]
	v_mfma_f32_16x16x32_bf16 v[40:43], v[176:179], v[188:191], v[40:43]
	v_mfma_f32_16x16x32_bf16 v[28:31], v[164:167], v[196:199], v[28:31]
	v_mfma_f32_16x16x32_bf16 v[24:27], v[176:179], v[196:199], v[24:27]
	v_mfma_f32_16x16x32_bf16 v[12:15], v[164:167], v[204:207], v[12:15]
	v_mfma_f32_16x16x32_bf16 v[8:11], v[176:179], v[204:207], v[8:11]
	v_mfma_f32_16x16x32_bf16 v[4:7], v[164:167], v[212:215], v[4:7]
	v_mfma_f32_16x16x32_bf16 v[0:3], v[176:179], v[212:215], v[0:3]
	v_mfma_f32_16x16x32_bf16 v[44:47], v[168:171], v[192:195], v[44:47]
	v_mfma_f32_16x16x32_bf16 v[40:43], v[180:183], v[192:195], v[40:43]
	v_mfma_f32_16x16x32_bf16 v[28:31], v[168:171], v[200:203], v[28:31]
	v_mfma_f32_16x16x32_bf16 v[24:27], v[180:183], v[200:203], v[24:27]
	v_mfma_f32_16x16x32_bf16 v[12:15], v[168:171], v[208:211], v[12:15]
	v_mfma_f32_16x16x32_bf16 v[8:11], v[180:183], v[208:211], v[8:11]
	v_mfma_f32_16x16x32_bf16 v[4:7], v[168:171], v[216:219], v[4:7]
	v_mfma_f32_16x16x32_bf16 v[0:3], v[180:183], v[216:219], v[0:3]
	s_barrier
	s_setprio 0
	s_add_i32 s52, s52, 2
	s_add_u32 s18, s18, 0x100
	s_addc_u32 s19, s19, 0
	s_cmp_gt_u32 s52, 29
	s_cbranch_scc0 .LBB0_250
	s_cmpk_lt_u32 s24, 0x100
	s_cbranch_scc0 .LBB0_253
	s_barrier

.LBB0_596:
	s_lshl_b32 s98, s56, 3
	s_add_i32 s98, s98, s2
	s_mul_i32 s98, s98, 3
	v_lshl_add_u32 v164, s56, 8, v172
	s_cmp_eq_u32 s87, 3
	v_mad_i64_i32 v[162:163], s[56:57], v164, s77, v[156:157]
	s_cselect_b64 s[62:63], -1, 0
	s_lshl_b32 s56, s2, 8
	s_ashr_i32 s57, s56, 31
	v_lshl_add_u64 v[2:3], s[56:57], 1, v[162:163]
	s_mov_b32 s7, s3
	v_lshl_add_u64 v[2:3], v[2:3], 0, s[6:7]
	v_lshl_add_u64 v[166:167], v[2:3], 0, v[160:161]
	s_add_i32 s7, s88, -2
	s_add_u32 s89, s60, 0x100
	v_mov_b32_e32 v1, v0
	v_ashrrev_i32_e32 v165, 31, v164
	s_addc_u32 s90, s61, 0
	v_lshl_add_u64 v[168:169], s[58:59], 0, v[152:153]
	v_lshl_add_u64 v[170:171], s[58:59], 0, v[154:155]
	s_mov_b32 s64, 0
	s_mov_b64 s[60:61], 0
	s_xor_b64 s[62:63], s[62:63], -1
	v_add_u32_e32 v1, s79, v173
	s_add_i32 s2, s64, 2
	ds_read_b128 v[132:135], v1
	ds_read_b128 v[136:139], v1 offset:1024
	ds_read_b128 v[140:143], v1 offset:2048
	ds_read_b128 v[178:181], v1 offset:3072
	v_add_u32_e32 v1, s80, v173
	s_add_u32 s65, s58, s60
	ds_read_b128 v[182:185], v1
	ds_read_b128 v[188:191], v1 offset:1024
	ds_read_b128 v[192:195], v1 offset:2048
	ds_read_b128 v[196:199], v1 offset:3072
	s_addc_u32 s66, s59, s61
	s_add_u32 s65, s65, 0x100
	s_addc_u32 s66, s66, 0
	s_add_u32 s75, s89, s60
	s_addc_u32 s91, s90, s61
	s_cmp_eq_u32 s7, s64
	s_cselect_b32 s67, s51, s66
	s_cselect_b32 s66, s50, s65
	s_cselect_b32 s65, s53, s91
	s_cselect_b32 s64, s52, s75
	v_lshl_add_u64 v[2:3], v[168:169], 0, s[60:61]
	s_add_i32 m0, s69, 0xc000
	ds_read_b128 v[200:203], v174
	ds_read_b128 v[204:207], v174 offset:1024
	ds_read_b128 v[208:211], v174 offset:2048
	ds_read_b128 v[212:215], v174 offset:3072
	ds_read_b128 v[216:219], v174 offset:4096
	ds_read_b128 v[220:223], v174 offset:5120
	ds_read_b128 v[224:227], v174 offset:6144
	ds_read_b128 v[228:231], v174 offset:7168
	global_load_lds_dwordx4 v[2:3], off
	v_lshl_add_u64 v[2:3], v[170:171], 0, s[60:61]
	s_add_i32 m0, s69, 0xe000
	s_nop 0
	global_load_lds_dwordx4 v[2:3], off
	s_waitcnt vmcnt(8)
	s_waitcnt lgkmcnt(0)
	s_waitcnt lgkmcnt(0)
	s_setprio 1
	s_barrier
	v_mfma_f32_16x16x32_bf16 v[128:131], v[132:135], v[200:203], 0
	v_mfma_f32_16x16x32_bf16 v[124:127], v[140:143], v[200:203], 0
	v_mfma_f32_16x16x32_bf16 v[112:115], v[132:135], v[208:211], 0
	v_mfma_f32_16x16x32_bf16 v[108:111], v[140:143], v[208:211], 0
	v_mfma_f32_16x16x32_bf16 v[96:99], v[132:135], v[216:219], 0
	v_mfma_f32_16x16x32_bf16 v[92:95], v[140:143], v[216:219], 0
	v_mfma_f32_16x16x32_bf16 v[80:83], v[132:135], v[224:227], 0
	v_mfma_f32_16x16x32_bf16 v[76:79], v[140:143], v[224:227], 0
	v_mfma_f32_16x16x32_bf16 v[128:131], v[136:139], v[204:207], v[128:131]
	v_mfma_f32_16x16x32_bf16 v[124:127], v[178:181], v[204:207], v[124:127]
	v_mfma_f32_16x16x32_bf16 v[112:115], v[136:139], v[212:215], v[112:115]
	v_mfma_f32_16x16x32_bf16 v[108:111], v[178:181], v[212:215], v[108:111]
	v_mfma_f32_16x16x32_bf16 v[96:99], v[136:139], v[220:223], v[96:99]
	v_mfma_f32_16x16x32_bf16 v[92:95], v[178:181], v[220:223], v[92:95]
	v_mfma_f32_16x16x32_bf16 v[80:83], v[136:139], v[228:231], v[80:83]
	v_mfma_f32_16x16x32_bf16 v[76:79], v[178:181], v[228:231], v[76:79]
	s_setprio 0
	s_setprio 1
	v_mfma_f32_16x16x32_bf16 v[120:123], v[182:185], v[200:203], 0
	v_mfma_f32_16x16x32_bf16 v[116:119], v[192:195], v[200:203], 0
	v_mfma_f32_16x16x32_bf16 v[104:107], v[182:185], v[208:211], 0
	v_mfma_f32_16x16x32_bf16 v[100:103], v[192:195], v[208:211], 0
	v_mfma_f32_16x16x32_bf16 v[88:91], v[182:185], v[216:219], 0
	v_mfma_f32_16x16x32_bf16 v[84:87], v[192:195], v[216:219], 0
	v_mfma_f32_16x16x32_bf16 v[72:75], v[182:185], v[224:227], 0
	v_mfma_f32_16x16x32_bf16 v[68:71], v[192:195], v[224:227], 0
	v_mfma_f32_16x16x32_bf16 v[120:123], v[188:191], v[204:207], v[120:123]
	v_mfma_f32_16x16x32_bf16 v[116:119], v[196:199], v[204:207], v[116:119]
	v_mfma_f32_16x16x32_bf16 v[104:107], v[188:191], v[212:215], v[104:107]
	v_mfma_f32_16x16x32_bf16 v[100:103], v[196:199], v[212:215], v[100:103]
	v_mfma_f32_16x16x32_bf16 v[88:91], v[188:191], v[220:223], v[88:91]
	v_mfma_f32_16x16x32_bf16 v[84:87], v[196:199], v[220:223], v[84:87]
	v_mfma_f32_16x16x32_bf16 v[72:75], v[188:191], v[228:231], v[72:75]
	v_mfma_f32_16x16x32_bf16 v[68:71], v[196:199], v[228:231], v[68:71]
	s_barrier
	s_setprio 0
	ds_read_b128 v[200:203], v174 offset:16384
	ds_read_b128 v[204:207], v174 offset:17408
	ds_read_b128 v[208:211], v174 offset:18432
	ds_read_b128 v[212:215], v174 offset:19456
	ds_read_b128 v[216:219], v174 offset:20480
	ds_read_b128 v[220:223], v174 offset:21504
	ds_read_b128 v[224:227], v174 offset:22528
	ds_read_b128 v[228:231], v174 offset:23552
	s_add_i32 s75, s79, s68
	s_mov_b32 m0, s75
	v_lshl_add_u64 v[232:233], s[64:65], 0, v[148:149]
	global_load_lds_dwordx4 v[232:233], off
	s_add_i32 m0, s75, 0x2000
	s_add_u32 s92, s64, 0xa0000
	v_lshl_add_u64 v[234:235], s[64:65], 0, v[144:145]
	s_addc_u32 s93, s65, 0
	s_add_i32 s75, s80, s68
	global_load_lds_dwordx4 v[234:235], off
	v_lshl_add_u64 v[2:3], s[92:93], 0, v[148:149]
	s_mov_b32 m0, s75
	v_lshl_add_u64 v[236:237], s[66:67], 0, v[150:151]
	global_load_lds_dwordx4 v[2:3], off
	v_lshl_add_u64 v[2:3], s[92:93], 0, v[144:145]
	s_add_i32 m0, s75, 0x2000
	v_lshl_add_u64 v[238:239], s[66:67], 0, v[146:147]
	global_load_lds_dwordx4 v[2:3], off
	s_mov_b32 m0, s69
	s_nop 0
	global_load_lds_dwordx4 v[236:237], off
	s_mov_b32 m0, s70
	s_nop 0
	global_load_lds_dwordx4 v[238:239], off
	s_waitcnt vmcnt(8)
	s_waitcnt lgkmcnt(0)
	s_waitcnt lgkmcnt(0)
	s_setprio 1
	s_barrier
	v_mfma_f32_16x16x32_bf16 v[64:67], v[132:135], v[200:203], 0
	v_mfma_f32_16x16x32_bf16 v[60:63], v[140:143], v[200:203], 0
	v_mfma_f32_16x16x32_bf16 v[48:51], v[132:135], v[208:211], 0
	v_mfma_f32_16x16x32_bf16 v[44:47], v[140:143], v[208:211], 0
	v_mfma_f32_16x16x32_bf16 v[32:35], v[132:135], v[216:219], 0
	v_mfma_f32_16x16x32_bf16 v[28:31], v[140:143], v[216:219], 0
	v_mfma_f32_16x16x32_bf16 v[16:19], v[132:135], v[224:227], 0
	v_mfma_f32_16x16x32_bf16 v[12:15], v[140:143], v[224:227], 0
	v_mfma_f32_16x16x32_bf16 v[64:67], v[136:139], v[204:207], v[64:67]
	v_mfma_f32_16x16x32_bf16 v[60:63], v[178:181], v[204:207], v[60:63]
	v_mfma_f32_16x16x32_bf16 v[48:51], v[136:139], v[212:215], v[48:51]
	v_mfma_f32_16x16x32_bf16 v[44:47], v[178:181], v[212:215], v[44:47]
	v_mfma_f32_16x16x32_bf16 v[32:35], v[136:139], v[220:223], v[32:35]
	v_mfma_f32_16x16x32_bf16 v[28:31], v[178:181], v[220:223], v[28:31]
	v_mfma_f32_16x16x32_bf16 v[16:19], v[136:139], v[228:231], v[16:19]
	v_mfma_f32_16x16x32_bf16 v[12:15], v[178:181], v[228:231], v[12:15]
	s_setprio 0
	s_setprio 1
	v_mfma_f32_16x16x32_bf16 v[56:59], v[182:185], v[200:203], 0
	v_mfma_f32_16x16x32_bf16 v[52:55], v[192:195], v[200:203], 0
	v_mfma_f32_16x16x32_bf16 v[40:43], v[182:185], v[208:211], 0
	v_mfma_f32_16x16x32_bf16 v[36:39], v[192:195], v[208:211], 0
	v_mfma_f32_16x16x32_bf16 v[24:27], v[182:185], v[216:219], 0
	v_mfma_f32_16x16x32_bf16 v[20:23], v[192:195], v[216:219], 0
	v_mfma_f32_16x16x32_bf16 v[8:11], v[182:185], v[224:227], 0
	v_mfma_f32_16x16x32_bf16 v[2:5], v[192:195], v[224:227], 0
	v_mfma_f32_16x16x32_bf16 v[56:59], v[188:191], v[204:207], v[56:59]
	v_mfma_f32_16x16x32_bf16 v[52:55], v[196:199], v[204:207], v[52:55]
	v_mfma_f32_16x16x32_bf16 v[40:43], v[188:191], v[212:215], v[40:43]
	v_mfma_f32_16x16x32_bf16 v[36:39], v[196:199], v[212:215], v[36:39]
	v_mfma_f32_16x16x32_bf16 v[24:27], v[188:191], v[220:223], v[24:27]
	v_mfma_f32_16x16x32_bf16 v[20:23], v[196:199], v[220:223], v[20:23]
	v_mfma_f32_16x16x32_bf16 v[8:11], v[188:191], v[228:231], v[8:11]
	v_mfma_f32_16x16x32_bf16 v[2:5], v[196:199], v[228:231], v[2:5]
	s_barrier
	s_setprio 0
	s_branch .Lpeel_mid_p3
	s_nop 0
	s_nop 0
	s_nop 0
	s_nop 0
	s_nop 0
	s_nop 0
	s_nop 0
	s_nop 0
	s_nop 0
	s_nop 0
	s_nop 0
	s_nop 0

.LBB0_599:
	v_add_u32_e32 v1, s79, v173
	s_add_i32 s2, s64, 2
	ds_read_b128 v[132:135], v1
	ds_read_b128 v[136:139], v1 offset:1024
	ds_read_b128 v[140:143], v1 offset:2048
	ds_read_b128 v[178:181], v1 offset:3072
	v_add_u32_e32 v1, s80, v173
	s_add_u32 s65, s58, s60
	ds_read_b128 v[182:185], v1
	ds_read_b128 v[188:191], v1 offset:1024
	ds_read_b128 v[192:195], v1 offset:2048
	ds_read_b128 v[196:199], v1 offset:3072
	s_addc_u32 s66, s59, s61
	s_add_u32 s65, s65, 0x100
	s_addc_u32 s66, s66, 0
	s_add_u32 s75, s89, s60
	s_addc_u32 s91, s90, s61
	s_cmp_eq_u32 s7, s64
	s_cselect_b32 s67, s51, s66
	s_cselect_b32 s66, s50, s65
	s_cselect_b32 s65, s53, s91
	s_cselect_b32 s64, s52, s75
	v_lshl_add_u64 v[2:3], v[168:169], 0, s[60:61]
	s_add_i32 m0, s69, 0xc000
	ds_read_b128 v[200:203], v174
	ds_read_b128 v[204:207], v174 offset:1024
	ds_read_b128 v[208:211], v174 offset:2048
	ds_read_b128 v[212:215], v174 offset:3072
	ds_read_b128 v[216:219], v174 offset:4096
	ds_read_b128 v[220:223], v174 offset:5120
	ds_read_b128 v[224:227], v174 offset:6144
	ds_read_b128 v[228:231], v174 offset:7168
	global_load_lds_dwordx4 v[2:3], off
	v_lshl_add_u64 v[2:3], v[170:171], 0, s[60:61]
	s_add_i32 m0, s69, 0xe000
	s_nop 0
	global_load_lds_dwordx4 v[2:3], off
	s_waitcnt vmcnt(8)
	s_waitcnt lgkmcnt(0)
	s_waitcnt lgkmcnt(0)
	s_setprio 1
	s_barrier
	v_mfma_f32_16x16x32_bf16 v[128:131], v[132:135], v[200:203], v[128:131]
	v_mfma_f32_16x16x32_bf16 v[124:127], v[140:143], v[200:203], v[124:127]
	v_mfma_f32_16x16x32_bf16 v[112:115], v[132:135], v[208:211], v[112:115]
	v_mfma_f32_16x16x32_bf16 v[108:111], v[140:143], v[208:211], v[108:111]
	v_mfma_f32_16x16x32_bf16 v[96:99], v[132:135], v[216:219], v[96:99]
	v_mfma_f32_16x16x32_bf16 v[92:95], v[140:143], v[216:219], v[92:95]
	v_mfma_f32_16x16x32_bf16 v[80:83], v[132:135], v[224:227], v[80:83]
	v_mfma_f32_16x16x32_bf16 v[76:79], v[140:143], v[224:227], v[76:79]
	v_mfma_f32_16x16x32_bf16 v[128:131], v[136:139], v[204:207], v[128:131]
	v_mfma_f32_16x16x32_bf16 v[124:127], v[178:181], v[204:207], v[124:127]
	v_mfma_f32_16x16x32_bf16 v[112:115], v[136:139], v[212:215], v[112:115]
	v_mfma_f32_16x16x32_bf16 v[108:111], v[178:181], v[212:215], v[108:111]
	v_mfma_f32_16x16x32_bf16 v[96:99], v[136:139], v[220:223], v[96:99]
	v_mfma_f32_16x16x32_bf16 v[92:95], v[178:181], v[220:223], v[92:95]
	v_mfma_f32_16x16x32_bf16 v[80:83], v[136:139], v[228:231], v[80:83]
	v_mfma_f32_16x16x32_bf16 v[76:79], v[178:181], v[228:231], v[76:79]
	s_setprio 0
	s_setprio 1
	v_mfma_f32_16x16x32_bf16 v[120:123], v[182:185], v[200:203], v[120:123]
	v_mfma_f32_16x16x32_bf16 v[116:119], v[192:195], v[200:203], v[116:119]
	v_mfma_f32_16x16x32_bf16 v[104:107], v[182:185], v[208:211], v[104:107]
	v_mfma_f32_16x16x32_bf16 v[100:103], v[192:195], v[208:211], v[100:103]
	v_mfma_f32_16x16x32_bf16 v[88:91], v[182:185], v[216:219], v[88:91]
	v_mfma_f32_16x16x32_bf16 v[84:87], v[192:195], v[216:219], v[84:87]
	v_mfma_f32_16x16x32_bf16 v[72:75], v[182:185], v[224:227], v[72:75]
	v_mfma_f32_16x16x32_bf16 v[68:71], v[192:195], v[224:227], v[68:71]
	v_mfma_f32_16x16x32_bf16 v[120:123], v[188:191], v[204:207], v[120:123]
	v_mfma_f32_16x16x32_bf16 v[116:119], v[196:199], v[204:207], v[116:119]
	v_mfma_f32_16x16x32_bf16 v[104:107], v[188:191], v[212:215], v[104:107]
	v_mfma_f32_16x16x32_bf16 v[100:103], v[196:199], v[212:215], v[100:103]
	v_mfma_f32_16x16x32_bf16 v[88:91], v[188:191], v[220:223], v[88:91]
	v_mfma_f32_16x16x32_bf16 v[84:87], v[196:199], v[220:223], v[84:87]
	v_mfma_f32_16x16x32_bf16 v[72:75], v[188:191], v[228:231], v[72:75]
	v_mfma_f32_16x16x32_bf16 v[68:71], v[196:199], v[228:231], v[68:71]
	s_barrier
	s_setprio 0
	ds_read_b128 v[200:203], v174 offset:16384
	ds_read_b128 v[204:207], v174 offset:17408
	ds_read_b128 v[208:211], v174 offset:18432
	ds_read_b128 v[212:215], v174 offset:19456
	ds_read_b128 v[216:219], v174 offset:20480
	ds_read_b128 v[220:223], v174 offset:21504
	ds_read_b128 v[224:227], v174 offset:22528
	ds_read_b128 v[228:231], v174 offset:23552
	s_add_i32 s75, s79, s68
	s_mov_b32 m0, s75
	v_lshl_add_u64 v[232:233], s[64:65], 0, v[148:149]
	global_load_lds_dwordx4 v[232:233], off
	s_add_i32 m0, s75, 0x2000
	s_add_u32 s92, s64, 0xa0000
	v_lshl_add_u64 v[234:235], s[64:65], 0, v[144:145]
	s_addc_u32 s93, s65, 0
	s_add_i32 s75, s80, s68
	global_load_lds_dwordx4 v[234:235], off
	v_lshl_add_u64 v[2:3], s[92:93], 0, v[148:149]
	s_mov_b32 m0, s75
	v_lshl_add_u64 v[236:237], s[66:67], 0, v[150:151]
	global_load_lds_dwordx4 v[2:3], off
	v_lshl_add_u64 v[2:3], s[92:93], 0, v[144:145]
	s_add_i32 m0, s75, 0x2000
	v_lshl_add_u64 v[238:239], s[66:67], 0, v[146:147]
	global_load_lds_dwordx4 v[2:3], off
	s_mov_b32 m0, s69
	s_nop 0
	global_load_lds_dwordx4 v[236:237], off
	s_mov_b32 m0, s70
	s_nop 0
	global_load_lds_dwordx4 v[238:239], off
	s_waitcnt vmcnt(8)
	s_waitcnt lgkmcnt(0)
	s_waitcnt lgkmcnt(0)
	s_setprio 1
	s_barrier
	v_mfma_f32_16x16x32_bf16 v[64:67], v[132:135], v[200:203], v[64:67]
	v_mfma_f32_16x16x32_bf16 v[60:63], v[140:143], v[200:203], v[60:63]
	v_mfma_f32_16x16x32_bf16 v[48:51], v[132:135], v[208:211], v[48:51]
	v_mfma_f32_16x16x32_bf16 v[44:47], v[140:143], v[208:211], v[44:47]
	v_mfma_f32_16x16x32_bf16 v[32:35], v[132:135], v[216:219], v[32:35]
	v_mfma_f32_16x16x32_bf16 v[28:31], v[140:143], v[216:219], v[28:31]
	v_mfma_f32_16x16x32_bf16 v[16:19], v[132:135], v[224:227], v[16:19]
	v_mfma_f32_16x16x32_bf16 v[12:15], v[140:143], v[224:227], v[12:15]
	v_mfma_f32_16x16x32_bf16 v[64:67], v[136:139], v[204:207], v[64:67]
	v_mfma_f32_16x16x32_bf16 v[60:63], v[178:181], v[204:207], v[60:63]
	v_mfma_f32_16x16x32_bf16 v[48:51], v[136:139], v[212:215], v[48:51]
	v_mfma_f32_16x16x32_bf16 v[44:47], v[178:181], v[212:215], v[44:47]
	v_mfma_f32_16x16x32_bf16 v[32:35], v[136:139], v[220:223], v[32:35]
	v_mfma_f32_16x16x32_bf16 v[28:31], v[178:181], v[220:223], v[28:31]
	v_mfma_f32_16x16x32_bf16 v[16:19], v[136:139], v[228:231], v[16:19]
	v_mfma_f32_16x16x32_bf16 v[12:15], v[178:181], v[228:231], v[12:15]
	s_setprio 0
	s_setprio 1
	v_mfma_f32_16x16x32_bf16 v[56:59], v[182:185], v[200:203], v[56:59]
	v_mfma_f32_16x16x32_bf16 v[52:55], v[192:195], v[200:203], v[52:55]
	v_mfma_f32_16x16x32_bf16 v[40:43], v[182:185], v[208:211], v[40:43]
	v_mfma_f32_16x16x32_bf16 v[36:39], v[192:195], v[208:211], v[36:39]
	v_mfma_f32_16x16x32_bf16 v[24:27], v[182:185], v[216:219], v[24:27]
	v_mfma_f32_16x16x32_bf16 v[20:23], v[192:195], v[216:219], v[20:23]
	v_mfma_f32_16x16x32_bf16 v[8:11], v[182:185], v[224:227], v[8:11]
	v_mfma_f32_16x16x32_bf16 v[2:5], v[192:195], v[224:227], v[4:7]
	v_mfma_f32_16x16x32_bf16 v[56:59], v[188:191], v[204:207], v[56:59]
	v_mfma_f32_16x16x32_bf16 v[52:55], v[196:199], v[204:207], v[52:55]
	v_mfma_f32_16x16x32_bf16 v[40:43], v[188:191], v[212:215], v[40:43]
	v_mfma_f32_16x16x32_bf16 v[36:39], v[196:199], v[212:215], v[36:39]
	v_mfma_f32_16x16x32_bf16 v[24:27], v[188:191], v[220:223], v[24:27]
	v_mfma_f32_16x16x32_bf16 v[20:23], v[196:199], v[220:223], v[20:23]
	v_mfma_f32_16x16x32_bf16 v[8:11], v[188:191], v[228:231], v[8:11]
	v_mfma_f32_16x16x32_bf16 v[2:5], v[196:199], v[228:231], v[2:5]
	s_barrier
	s_setprio 0
.Lpeel_mid_p3:
	s_add_i32 s75, 0, 0x18000
	v_add_u32_e32 v1, s75, v173
	s_add_i32 s91, 0, 0x1c000
	ds_read_b128 v[132:135], v1
	ds_read_b128 v[136:139], v1 offset:1024
	ds_read_b128 v[140:143], v1 offset:2048
	ds_read_b128 v[178:181], v1 offset:3072
	v_add_u32_e32 v1, s91, v173
	ds_read_b128 v[182:185], v1
	ds_read_b128 v[188:191], v1 offset:1024
	ds_read_b128 v[192:195], v1 offset:2048
	ds_read_b128 v[196:199], v1 offset:3072
	s_add_u32 s66, s66, 0xa0000
	s_addc_u32 s67, s67, 0
	s_mov_b32 m0, s71
	v_lshl_add_u64 v[6:7], s[66:67], 0, v[150:151]
	ds_read_b128 v[200:203], v174 offset:32768
	ds_read_b128 v[204:207], v174 offset:33792
	ds_read_b128 v[208:211], v174 offset:34816
	ds_read_b128 v[212:215], v174 offset:35840
	ds_read_b128 v[216:219], v174 offset:36864
	ds_read_b128 v[220:223], v174 offset:37888
	ds_read_b128 v[224:227], v174 offset:38912
	ds_read_b128 v[228:231], v174 offset:39936
	global_load_lds_dwordx4 v[6:7], off
	v_lshl_add_u64 v[6:7], s[66:67], 0, v[146:147]
	s_mov_b32 m0, s72
	s_nop 0
	global_load_lds_dwordx4 v[6:7], off
	s_waitcnt vmcnt(8)
	s_waitcnt lgkmcnt(0)
	s_waitcnt lgkmcnt(0)
	s_setprio 1
	s_barrier
	v_mfma_f32_16x16x32_bf16 v[128:131], v[132:135], v[200:203], v[128:131]
	v_mfma_f32_16x16x32_bf16 v[124:127], v[140:143], v[200:203], v[124:127]
	v_mfma_f32_16x16x32_bf16 v[112:115], v[132:135], v[208:211], v[112:115]
	v_mfma_f32_16x16x32_bf16 v[108:111], v[140:143], v[208:211], v[108:111]
	v_mfma_f32_16x16x32_bf16 v[96:99], v[132:135], v[216:219], v[96:99]
	v_mfma_f32_16x16x32_bf16 v[92:95], v[140:143], v[216:219], v[92:95]
	v_mfma_f32_16x16x32_bf16 v[80:83], v[132:135], v[224:227], v[80:83]
	v_mfma_f32_16x16x32_bf16 v[76:79], v[140:143], v[224:227], v[76:79]
	v_mfma_f32_16x16x32_bf16 v[128:131], v[136:139], v[204:207], v[128:131]
	v_mfma_f32_16x16x32_bf16 v[124:127], v[178:181], v[204:207], v[124:127]
	v_mfma_f32_16x16x32_bf16 v[112:115], v[136:139], v[212:215], v[112:115]
	v_mfma_f32_16x16x32_bf16 v[108:111], v[178:181], v[212:215], v[108:111]
	v_mfma_f32_16x16x32_bf16 v[96:99], v[136:139], v[220:223], v[96:99]
	v_mfma_f32_16x16x32_bf16 v[92:95], v[178:181], v[220:223], v[92:95]
	v_mfma_f32_16x16x32_bf16 v[80:83], v[136:139], v[228:231], v[80:83]
	v_mfma_f32_16x16x32_bf16 v[76:79], v[178:181], v[228:231], v[76:79]
	s_setprio 0
	s_setprio 1
	v_mfma_f32_16x16x32_bf16 v[120:123], v[182:185], v[200:203], v[120:123]
	v_mfma_f32_16x16x32_bf16 v[116:119], v[192:195], v[200:203], v[116:119]
	v_mfma_f32_16x16x32_bf16 v[104:107], v[182:185], v[208:211], v[104:107]
	v_mfma_f32_16x16x32_bf16 v[100:103], v[192:195], v[208:211], v[100:103]
	v_mfma_f32_16x16x32_bf16 v[88:91], v[182:185], v[216:219], v[88:91]
	v_mfma_f32_16x16x32_bf16 v[84:87], v[192:195], v[216:219], v[84:87]
	v_mfma_f32_16x16x32_bf16 v[72:75], v[182:185], v[224:227], v[72:75]
	v_mfma_f32_16x16x32_bf16 v[68:71], v[192:195], v[224:227], v[68:71]
	v_mfma_f32_16x16x32_bf16 v[120:123], v[188:191], v[204:207], v[120:123]
	v_mfma_f32_16x16x32_bf16 v[116:119], v[196:199], v[204:207], v[116:119]
	v_mfma_f32_16x16x32_bf16 v[104:107], v[188:191], v[212:215], v[104:107]
	v_mfma_f32_16x16x32_bf16 v[100:103], v[196:199], v[212:215], v[100:103]
	v_mfma_f32_16x16x32_bf16 v[88:91], v[188:191], v[220:223], v[88:91]
	v_mfma_f32_16x16x32_bf16 v[84:87], v[196:199], v[220:223], v[84:87]
	v_mfma_f32_16x16x32_bf16 v[72:75], v[188:191], v[228:231], v[72:75]
	v_mfma_f32_16x16x32_bf16 v[68:71], v[196:199], v[228:231], v[68:71]
	s_barrier
	s_setprio 0
	ds_read_b128 v[200:203], v174 offset:49152
	ds_read_b128 v[204:207], v174 offset:50176
	ds_read_b128 v[208:211], v174 offset:51200
	ds_read_b128 v[212:215], v174 offset:52224
	ds_read_b128 v[216:219], v174 offset:53248
	ds_read_b128 v[220:223], v174 offset:54272
	ds_read_b128 v[224:227], v174 offset:55296
	ds_read_b128 v[228:231], v174 offset:56320
	s_add_i32 s66, s75, s68
	s_mov_b32 m0, s66
	v_lshl_add_u64 v[6:7], v[232:233], 0, s[14:15]
	global_load_lds_dwordx4 v[6:7], off
	s_add_i32 m0, s66, 0x2000
	s_add_u32 s64, s64, 0xa0080
	v_lshl_add_u64 v[6:7], v[234:235], 0, s[14:15]
	s_addc_u32 s65, s65, 0
	s_add_i32 s66, s91, s68
	global_load_lds_dwordx4 v[6:7], off
	v_lshl_add_u64 v[6:7], s[64:65], 0, v[148:149]
	s_mov_b32 m0, s66
	s_nop 0
	global_load_lds_dwordx4 v[6:7], off
	v_lshl_add_u64 v[6:7], s[64:65], 0, v[144:145]
	s_add_i32 m0, s66, 0x2000
	s_nop 0
	global_load_lds_dwordx4 v[6:7], off
	v_lshl_add_u64 v[6:7], v[236:237], 0, s[14:15]
	s_mov_b32 m0, s73
	s_nop 0
	global_load_lds_dwordx4 v[6:7], off
	v_lshl_add_u64 v[6:7], v[238:239], 0, s[14:15]
	s_mov_b32 m0, s76
	s_nop 0
	global_load_lds_dwordx4 v[6:7], off
	s_waitcnt vmcnt(8)
	s_waitcnt lgkmcnt(0)
	s_waitcnt lgkmcnt(0)
	s_setprio 1
	s_barrier
	v_mfma_f32_16x16x32_bf16 v[64:67], v[132:135], v[200:203], v[64:67]
	v_mfma_f32_16x16x32_bf16 v[60:63], v[140:143], v[200:203], v[60:63]
	v_mfma_f32_16x16x32_bf16 v[48:51], v[132:135], v[208:211], v[48:51]
	v_mfma_f32_16x16x32_bf16 v[44:47], v[140:143], v[208:211], v[44:47]
	v_mfma_f32_16x16x32_bf16 v[32:35], v[132:135], v[216:219], v[32:35]
	v_mfma_f32_16x16x32_bf16 v[28:31], v[140:143], v[216:219], v[28:31]
	v_mfma_f32_16x16x32_bf16 v[16:19], v[132:135], v[224:227], v[16:19]
	v_mfma_f32_16x16x32_bf16 v[12:15], v[140:143], v[224:227], v[12:15]
	v_mfma_f32_16x16x32_bf16 v[64:67], v[136:139], v[204:207], v[64:67]
	v_mfma_f32_16x16x32_bf16 v[60:63], v[178:181], v[204:207], v[60:63]
	v_mfma_f32_16x16x32_bf16 v[48:51], v[136:139], v[212:215], v[48:51]
	v_mfma_f32_16x16x32_bf16 v[44:47], v[178:181], v[212:215], v[44:47]
	v_mfma_f32_16x16x32_bf16 v[32:35], v[136:139], v[220:223], v[32:35]
	v_mfma_f32_16x16x32_bf16 v[28:31], v[178:181], v[220:223], v[28:31]
	v_mfma_f32_16x16x32_bf16 v[16:19], v[136:139], v[228:231], v[16:19]
	v_mfma_f32_16x16x32_bf16 v[12:15], v[178:181], v[228:231], v[12:15]
	s_setprio 0
	s_setprio 1
	v_mfma_f32_16x16x32_bf16 v[56:59], v[182:185], v[200:203], v[56:59]
	v_mfma_f32_16x16x32_bf16 v[52:55], v[192:195], v[200:203], v[52:55]
	v_mfma_f32_16x16x32_bf16 v[40:43], v[182:185], v[208:211], v[40:43]
	s_or_b64 vcc, s[18:19], s[62:63]
	v_mfma_f32_16x16x32_bf16 v[36:39], v[192:195], v[208:211], v[36:39]
	s_cmp_eq_u32 s2, 16
	v_mfma_f32_16x16x32_bf16 v[24:27], v[182:185], v[216:219], v[24:27]
	s_cselect_b32 s100, 1, 0
	v_mfma_f32_16x16x32_bf16 v[20:23], v[192:195], v[216:219], v[20:23]
	s_cmp_eq_u32 s2, 24
	v_mfma_f32_16x16x32_bf16 v[6:9], v[182:185], v[224:227], v[8:11]
	s_cselect_b32 s101, 1, 0
	v_mfma_f32_16x16x32_bf16 v[2:5], v[192:195], v[224:227], v[2:5]
	s_or_b32 s100, s100, s101
	v_mfma_f32_16x16x32_bf16 v[56:59], v[188:191], v[204:207], v[56:59]
	s_cmp_eq_u64 vcc, 0
	v_mfma_f32_16x16x32_bf16 v[52:55], v[196:199], v[204:207], v[52:55]
	s_cselect_b32 s100, s100, 0
	v_mfma_f32_16x16x32_bf16 v[40:43], v[188:191], v[212:215], v[40:43]
	s_cmp_lg_u32 s100, 0
	v_mfma_f32_16x16x32_bf16 v[36:39], v[196:199], v[212:215], v[36:39]
	v_mfma_f32_16x16x32_bf16 v[24:27], v[188:191], v[220:223], v[24:27]
	v_mfma_f32_16x16x32_bf16 v[20:23], v[196:199], v[220:223], v[20:23]
	v_mfma_f32_16x16x32_bf16 v[8:11], v[188:191], v[228:231], v[6:9]
	v_mfma_f32_16x16x32_bf16 v[4:7], v[196:199], v[228:231], v[2:5]
	s_setprio 0
	s_cbranch_scc0 .Lhk_skipB

.LBB0_671:
	s_add_u32 s6, s6, 0x80080
	s_addc_u32 s7, s7, 0
	s_add_u32 s5, s40, 0x100
	s_addc_u32 s25, s41, 0
	s_mov_b32 s56, -2
	ds_read_b128 v[128:131], v185
	ds_read_b128 v[132:135], v185 offset:1024
	ds_read_b128 v[136:139], v185 offset:2048
	ds_read_b128 v[140:143], v185 offset:3072
	ds_read_b128 v[162:165], v186
	ds_read_b128 v[166:169], v186 offset:1024
	ds_read_b128 v[170:173], v186 offset:2048
	ds_read_b128 v[174:177], v186 offset:3072
	s_add_u32 s38, s6, 0xfff80080
	s_addc_u32 s39, s7, -1
	s_cmp_eq_u32 s56, 28
	s_cselect_b32 s41, s27, s39
	s_cselect_b32 s40, s26, s38
	s_cselect_b32 s39, s23, s25
	s_cselect_b32 s38, s22, s5
	v_lshl_add_u64 v[182:183], s[6:7], 0, v[158:159]
	s_add_i32 m0, s42, 0xc000
	ds_read_b128 v[178:181], v188
	ds_read_b128 v[192:195], v188 offset:1024
	ds_read_b128 v[196:199], v188 offset:2048
	ds_read_b128 v[200:203], v188 offset:3072
	ds_read_b128 v[204:207], v188 offset:4096
	ds_read_b128 v[208:211], v188 offset:5120
	ds_read_b128 v[212:215], v188 offset:6144
	ds_read_b128 v[216:219], v188 offset:7168
	global_load_lds_dwordx4 v[182:183], off
	v_lshl_add_u64 v[182:183], s[6:7], 0, v[160:161]
	s_add_i32 m0, s42, 0xe000
	s_nop 0
	global_load_lds_dwordx4 v[182:183], off
	s_waitcnt vmcnt(8)
	s_waitcnt lgkmcnt(0)
	s_waitcnt lgkmcnt(0)
	s_setprio 1
	s_barrier
	v_mfma_f32_16x16x32_bf16 v[124:127], v[128:131], v[178:181], 0
	v_mfma_f32_16x16x32_bf16 v[120:123], v[136:139], v[178:181], 0
	v_mfma_f32_16x16x32_bf16 v[108:111], v[128:131], v[196:199], 0
	v_mfma_f32_16x16x32_bf16 v[104:107], v[136:139], v[196:199], 0
	v_mfma_f32_16x16x32_bf16 v[92:95], v[128:131], v[204:207], 0
	v_mfma_f32_16x16x32_bf16 v[88:91], v[136:139], v[204:207], 0
	v_mfma_f32_16x16x32_bf16 v[76:79], v[128:131], v[212:215], 0
	v_mfma_f32_16x16x32_bf16 v[72:75], v[136:139], v[212:215], 0
	v_mfma_f32_16x16x32_bf16 v[124:127], v[132:135], v[192:195], v[124:127]
	v_mfma_f32_16x16x32_bf16 v[120:123], v[140:143], v[192:195], v[120:123]
	v_mfma_f32_16x16x32_bf16 v[108:111], v[132:135], v[200:203], v[108:111]
	v_mfma_f32_16x16x32_bf16 v[104:107], v[140:143], v[200:203], v[104:107]
	v_mfma_f32_16x16x32_bf16 v[92:95], v[132:135], v[208:211], v[92:95]
	v_mfma_f32_16x16x32_bf16 v[88:91], v[140:143], v[208:211], v[88:91]
	v_mfma_f32_16x16x32_bf16 v[76:79], v[132:135], v[216:219], v[76:79]
	v_mfma_f32_16x16x32_bf16 v[72:75], v[140:143], v[216:219], v[72:75]
	s_setprio 0
	s_setprio 1
	v_mfma_f32_16x16x32_bf16 v[116:119], v[162:165], v[178:181], 0
	v_mfma_f32_16x16x32_bf16 v[112:115], v[170:173], v[178:181], 0
	v_mfma_f32_16x16x32_bf16 v[100:103], v[162:165], v[196:199], 0
	v_mfma_f32_16x16x32_bf16 v[96:99], v[170:173], v[196:199], 0
	v_mfma_f32_16x16x32_bf16 v[84:87], v[162:165], v[204:207], 0
	v_mfma_f32_16x16x32_bf16 v[80:83], v[170:173], v[204:207], 0
	v_mfma_f32_16x16x32_bf16 v[68:71], v[162:165], v[212:215], 0
	v_mfma_f32_16x16x32_bf16 v[64:67], v[170:173], v[212:215], 0
	v_mfma_f32_16x16x32_bf16 v[116:119], v[166:169], v[192:195], v[116:119]
	v_mfma_f32_16x16x32_bf16 v[112:115], v[174:177], v[192:195], v[112:115]
	v_mfma_f32_16x16x32_bf16 v[100:103], v[166:169], v[200:203], v[100:103]
	v_mfma_f32_16x16x32_bf16 v[96:99], v[174:177], v[200:203], v[96:99]
	v_mfma_f32_16x16x32_bf16 v[84:87], v[166:169], v[208:211], v[84:87]
	v_mfma_f32_16x16x32_bf16 v[80:83], v[174:177], v[208:211], v[80:83]
	v_mfma_f32_16x16x32_bf16 v[68:71], v[166:169], v[216:219], v[68:71]
	v_mfma_f32_16x16x32_bf16 v[64:67], v[174:177], v[216:219], v[64:67]
	s_barrier
	s_setprio 0
	ds_read_b128 v[178:181], v188 offset:16384
	ds_read_b128 v[192:195], v188 offset:17408
	ds_read_b128 v[196:199], v188 offset:18432
	ds_read_b128 v[200:203], v188 offset:19456
	ds_read_b128 v[204:207], v188 offset:20480
	ds_read_b128 v[208:211], v188 offset:21504
	ds_read_b128 v[212:215], v188 offset:22528
	ds_read_b128 v[216:219], v188 offset:23552
	s_add_i32 s57, s51, s35
	s_mov_b32 m0, s57
	v_lshl_add_u64 v[182:183], s[38:39], 0, v[148:149]
	global_load_lds_dwordx4 v[182:183], off
	s_add_i32 m0, s57, 0x2000
	s_add_u32 s58, s38, 0x80000
	v_lshl_add_u64 v[220:221], s[38:39], 0, v[144:145]
	s_addc_u32 s59, s39, 0
	s_add_i32 s57, s52, s35
	global_load_lds_dwordx4 v[220:221], off
	v_lshl_add_u64 v[222:223], s[58:59], 0, v[148:149]
	s_mov_b32 m0, s57
	v_lshl_add_u64 v[224:225], s[40:41], 0, v[146:147]
	global_load_lds_dwordx4 v[222:223], off
	v_lshl_add_u64 v[222:223], s[58:59], 0, v[144:145]
	s_add_i32 m0, s57, 0x2000
	s_nop 0
	global_load_lds_dwordx4 v[222:223], off
	v_lshl_add_u64 v[222:223], s[40:41], 0, v[150:151]
	s_mov_b32 m0, s42
	s_nop 0
	global_load_lds_dwordx4 v[222:223], off
	s_mov_b32 m0, s43
	s_nop 0
	global_load_lds_dwordx4 v[224:225], off
	s_waitcnt vmcnt(8)
	s_waitcnt lgkmcnt(0)
	s_waitcnt lgkmcnt(0)
	s_setprio 1
	s_barrier
	v_mfma_f32_16x16x32_bf16 v[60:63], v[128:131], v[178:181], 0
	v_mfma_f32_16x16x32_bf16 v[56:59], v[136:139], v[178:181], 0
	v_mfma_f32_16x16x32_bf16 v[44:47], v[128:131], v[196:199], 0
	v_mfma_f32_16x16x32_bf16 v[40:43], v[136:139], v[196:199], 0
	v_mfma_f32_16x16x32_bf16 v[28:31], v[128:131], v[204:207], 0
	v_mfma_f32_16x16x32_bf16 v[24:27], v[136:139], v[204:207], 0
	v_mfma_f32_16x16x32_bf16 v[12:15], v[128:131], v[212:215], 0
	v_mfma_f32_16x16x32_bf16 v[8:11], v[136:139], v[212:215], 0
	v_mfma_f32_16x16x32_bf16 v[60:63], v[132:135], v[192:195], v[60:63]
	v_mfma_f32_16x16x32_bf16 v[56:59], v[140:143], v[192:195], v[56:59]
	v_mfma_f32_16x16x32_bf16 v[44:47], v[132:135], v[200:203], v[44:47]
	v_mfma_f32_16x16x32_bf16 v[40:43], v[140:143], v[200:203], v[40:43]
	v_mfma_f32_16x16x32_bf16 v[28:31], v[132:135], v[208:211], v[28:31]
	v_mfma_f32_16x16x32_bf16 v[24:27], v[140:143], v[208:211], v[24:27]
	v_mfma_f32_16x16x32_bf16 v[12:15], v[132:135], v[216:219], v[12:15]
	v_mfma_f32_16x16x32_bf16 v[8:11], v[140:143], v[216:219], v[8:11]
	s_setprio 0
	s_setprio 1
	v_mfma_f32_16x16x32_bf16 v[52:55], v[162:165], v[178:181], 0
	v_mfma_f32_16x16x32_bf16 v[48:51], v[170:173], v[178:181], 0
	v_mfma_f32_16x16x32_bf16 v[36:39], v[162:165], v[196:199], 0
	v_mfma_f32_16x16x32_bf16 v[32:35], v[170:173], v[196:199], 0
	v_mfma_f32_16x16x32_bf16 v[20:23], v[162:165], v[204:207], 0
	v_mfma_f32_16x16x32_bf16 v[16:19], v[170:173], v[204:207], 0
	v_mfma_f32_16x16x32_bf16 v[4:7], v[162:165], v[212:215], 0
	v_mfma_f32_16x16x32_bf16 v[0:3], v[170:173], v[212:215], 0
	v_mfma_f32_16x16x32_bf16 v[52:55], v[166:169], v[192:195], v[52:55]
	v_mfma_f32_16x16x32_bf16 v[48:51], v[174:177], v[192:195], v[48:51]
	v_mfma_f32_16x16x32_bf16 v[36:39], v[166:169], v[200:203], v[36:39]
	v_mfma_f32_16x16x32_bf16 v[32:35], v[174:177], v[200:203], v[32:35]
	v_mfma_f32_16x16x32_bf16 v[20:23], v[166:169], v[208:211], v[20:23]
	v_mfma_f32_16x16x32_bf16 v[16:19], v[174:177], v[208:211], v[16:19]
	v_mfma_f32_16x16x32_bf16 v[4:7], v[166:169], v[216:219], v[4:7]
	v_mfma_f32_16x16x32_bf16 v[0:3], v[174:177], v[216:219], v[0:3]
	s_barrier
	s_setprio 0
	s_branch .Lpeel_mid_p4
	s_nop 0
	s_nop 0
	s_nop 0
	s_nop 0
	s_nop 0
	s_nop 0
	s_nop 0
	s_nop 0
	s_nop 0
	s_nop 0
	s_nop 0
	s_nop 0
	s_nop 0
	s_nop 0
.LBB0_672:
	ds_read_b128 v[128:131], v185
	ds_read_b128 v[132:135], v185 offset:1024
	ds_read_b128 v[136:139], v185 offset:2048
	ds_read_b128 v[140:143], v185 offset:3072
	ds_read_b128 v[162:165], v186
	ds_read_b128 v[166:169], v186 offset:1024
	ds_read_b128 v[170:173], v186 offset:2048
	ds_read_b128 v[174:177], v186 offset:3072
	s_add_u32 s38, s6, 0xfff80080
	s_addc_u32 s39, s7, -1
	s_cmp_eq_u32 s56, 28
	s_cselect_b32 s41, s27, s39
	s_cselect_b32 s40, s26, s38
	s_cselect_b32 s39, s23, s25
	s_cselect_b32 s38, s22, s5
	v_lshl_add_u64 v[182:183], s[6:7], 0, v[158:159]
	s_add_i32 m0, s42, 0xc000
	ds_read_b128 v[178:181], v188
	ds_read_b128 v[192:195], v188 offset:1024
	ds_read_b128 v[196:199], v188 offset:2048
	ds_read_b128 v[200:203], v188 offset:3072
	ds_read_b128 v[204:207], v188 offset:4096
	ds_read_b128 v[208:211], v188 offset:5120
	ds_read_b128 v[212:215], v188 offset:6144
	ds_read_b128 v[216:219], v188 offset:7168
	global_load_lds_dwordx4 v[182:183], off
	v_lshl_add_u64 v[182:183], s[6:7], 0, v[160:161]
	s_add_i32 m0, s42, 0xe000
	s_nop 0
	global_load_lds_dwordx4 v[182:183], off
	s_waitcnt vmcnt(8)
	s_waitcnt lgkmcnt(0)
	s_waitcnt lgkmcnt(0)
	s_setprio 1
	s_barrier
	v_mfma_f32_16x16x32_bf16 v[124:127], v[128:131], v[178:181], v[124:127]
	v_mfma_f32_16x16x32_bf16 v[120:123], v[136:139], v[178:181], v[120:123]
	v_mfma_f32_16x16x32_bf16 v[108:111], v[128:131], v[196:199], v[108:111]
	v_mfma_f32_16x16x32_bf16 v[104:107], v[136:139], v[196:199], v[104:107]
	v_mfma_f32_16x16x32_bf16 v[92:95], v[128:131], v[204:207], v[92:95]
	v_mfma_f32_16x16x32_bf16 v[88:91], v[136:139], v[204:207], v[88:91]
	v_mfma_f32_16x16x32_bf16 v[76:79], v[128:131], v[212:215], v[76:79]
	v_mfma_f32_16x16x32_bf16 v[72:75], v[136:139], v[212:215], v[72:75]
	v_mfma_f32_16x16x32_bf16 v[124:127], v[132:135], v[192:195], v[124:127]
	v_mfma_f32_16x16x32_bf16 v[120:123], v[140:143], v[192:195], v[120:123]
	v_mfma_f32_16x16x32_bf16 v[108:111], v[132:135], v[200:203], v[108:111]
	v_mfma_f32_16x16x32_bf16 v[104:107], v[140:143], v[200:203], v[104:107]
	v_mfma_f32_16x16x32_bf16 v[92:95], v[132:135], v[208:211], v[92:95]
	v_mfma_f32_16x16x32_bf16 v[88:91], v[140:143], v[208:211], v[88:91]
	v_mfma_f32_16x16x32_bf16 v[76:79], v[132:135], v[216:219], v[76:79]
	v_mfma_f32_16x16x32_bf16 v[72:75], v[140:143], v[216:219], v[72:75]
	s_setprio 0
	s_setprio 1
	v_mfma_f32_16x16x32_bf16 v[116:119], v[162:165], v[178:181], v[116:119]
	v_mfma_f32_16x16x32_bf16 v[112:115], v[170:173], v[178:181], v[112:115]
	v_mfma_f32_16x16x32_bf16 v[100:103], v[162:165], v[196:199], v[100:103]
	v_mfma_f32_16x16x32_bf16 v[96:99], v[170:173], v[196:199], v[96:99]
	v_mfma_f32_16x16x32_bf16 v[84:87], v[162:165], v[204:207], v[84:87]
	v_mfma_f32_16x16x32_bf16 v[80:83], v[170:173], v[204:207], v[80:83]
	v_mfma_f32_16x16x32_bf16 v[68:71], v[162:165], v[212:215], v[68:71]
	v_mfma_f32_16x16x32_bf16 v[64:67], v[170:173], v[212:215], v[64:67]
	v_mfma_f32_16x16x32_bf16 v[116:119], v[166:169], v[192:195], v[116:119]
	v_mfma_f32_16x16x32_bf16 v[112:115], v[174:177], v[192:195], v[112:115]
	v_mfma_f32_16x16x32_bf16 v[100:103], v[166:169], v[200:203], v[100:103]
	v_mfma_f32_16x16x32_bf16 v[96:99], v[174:177], v[200:203], v[96:99]
	v_mfma_f32_16x16x32_bf16 v[84:87], v[166:169], v[208:211], v[84:87]
	v_mfma_f32_16x16x32_bf16 v[80:83], v[174:177], v[208:211], v[80:83]
	v_mfma_f32_16x16x32_bf16 v[68:71], v[166:169], v[216:219], v[68:71]
	v_mfma_f32_16x16x32_bf16 v[64:67], v[174:177], v[216:219], v[64:67]
	s_barrier
	s_setprio 0
	ds_read_b128 v[178:181], v188 offset:16384
	ds_read_b128 v[192:195], v188 offset:17408
	ds_read_b128 v[196:199], v188 offset:18432
	ds_read_b128 v[200:203], v188 offset:19456
	ds_read_b128 v[204:207], v188 offset:20480
	ds_read_b128 v[208:211], v188 offset:21504
	ds_read_b128 v[212:215], v188 offset:22528
	ds_read_b128 v[216:219], v188 offset:23552
	s_add_i32 s57, s51, s35
	s_mov_b32 m0, s57
	v_lshl_add_u64 v[182:183], s[38:39], 0, v[148:149]
	global_load_lds_dwordx4 v[182:183], off
	s_add_i32 m0, s57, 0x2000
	s_add_u32 s58, s38, 0x80000
	v_lshl_add_u64 v[220:221], s[38:39], 0, v[144:145]
	s_addc_u32 s59, s39, 0
	s_add_i32 s57, s52, s35
	global_load_lds_dwordx4 v[220:221], off
	v_lshl_add_u64 v[222:223], s[58:59], 0, v[148:149]
	s_mov_b32 m0, s57
	v_lshl_add_u64 v[224:225], s[40:41], 0, v[146:147]
	global_load_lds_dwordx4 v[222:223], off
	v_lshl_add_u64 v[222:223], s[58:59], 0, v[144:145]
	s_add_i32 m0, s57, 0x2000
	s_nop 0
	global_load_lds_dwordx4 v[222:223], off
	v_lshl_add_u64 v[222:223], s[40:41], 0, v[150:151]
	s_mov_b32 m0, s42
	s_nop 0
	global_load_lds_dwordx4 v[222:223], off
	s_mov_b32 m0, s43
	s_nop 0
	global_load_lds_dwordx4 v[224:225], off
	s_waitcnt vmcnt(8)
	s_waitcnt lgkmcnt(0)
	s_waitcnt lgkmcnt(0)
	s_setprio 1
	s_barrier
	v_mfma_f32_16x16x32_bf16 v[60:63], v[128:131], v[178:181], v[60:63]
	v_mfma_f32_16x16x32_bf16 v[56:59], v[136:139], v[178:181], v[56:59]
	v_mfma_f32_16x16x32_bf16 v[44:47], v[128:131], v[196:199], v[44:47]
	v_mfma_f32_16x16x32_bf16 v[40:43], v[136:139], v[196:199], v[40:43]
	v_mfma_f32_16x16x32_bf16 v[28:31], v[128:131], v[204:207], v[28:31]
	v_mfma_f32_16x16x32_bf16 v[24:27], v[136:139], v[204:207], v[24:27]
	v_mfma_f32_16x16x32_bf16 v[12:15], v[128:131], v[212:215], v[12:15]
	v_mfma_f32_16x16x32_bf16 v[8:11], v[136:139], v[212:215], v[8:11]
	v_mfma_f32_16x16x32_bf16 v[60:63], v[132:135], v[192:195], v[60:63]
	v_mfma_f32_16x16x32_bf16 v[56:59], v[140:143], v[192:195], v[56:59]
	v_mfma_f32_16x16x32_bf16 v[44:47], v[132:135], v[200:203], v[44:47]
	v_mfma_f32_16x16x32_bf16 v[40:43], v[140:143], v[200:203], v[40:43]
	v_mfma_f32_16x16x32_bf16 v[28:31], v[132:135], v[208:211], v[28:31]
	v_mfma_f32_16x16x32_bf16 v[24:27], v[140:143], v[208:211], v[24:27]
	v_mfma_f32_16x16x32_bf16 v[12:15], v[132:135], v[216:219], v[12:15]
	v_mfma_f32_16x16x32_bf16 v[8:11], v[140:143], v[216:219], v[8:11]
	s_setprio 0
	s_setprio 1
	v_mfma_f32_16x16x32_bf16 v[52:55], v[162:165], v[178:181], v[52:55]
	v_mfma_f32_16x16x32_bf16 v[48:51], v[170:173], v[178:181], v[48:51]
	v_mfma_f32_16x16x32_bf16 v[36:39], v[162:165], v[196:199], v[36:39]
	v_mfma_f32_16x16x32_bf16 v[32:35], v[170:173], v[196:199], v[32:35]
	v_mfma_f32_16x16x32_bf16 v[20:23], v[162:165], v[204:207], v[20:23]
	v_mfma_f32_16x16x32_bf16 v[16:19], v[170:173], v[204:207], v[16:19]
	v_mfma_f32_16x16x32_bf16 v[4:7], v[162:165], v[212:215], v[4:7]
	v_mfma_f32_16x16x32_bf16 v[0:3], v[170:173], v[212:215], v[0:3]
	v_mfma_f32_16x16x32_bf16 v[52:55], v[166:169], v[192:195], v[52:55]
	v_mfma_f32_16x16x32_bf16 v[48:51], v[174:177], v[192:195], v[48:51]
	v_mfma_f32_16x16x32_bf16 v[36:39], v[166:169], v[200:203], v[36:39]
	v_mfma_f32_16x16x32_bf16 v[32:35], v[174:177], v[200:203], v[32:35]
	v_mfma_f32_16x16x32_bf16 v[20:23], v[166:169], v[208:211], v[20:23]
	v_mfma_f32_16x16x32_bf16 v[16:19], v[174:177], v[208:211], v[16:19]
	v_mfma_f32_16x16x32_bf16 v[4:7], v[166:169], v[216:219], v[4:7]
	v_mfma_f32_16x16x32_bf16 v[0:3], v[174:177], v[216:219], v[0:3]
	s_barrier
	s_setprio 0
.Lpeel_mid_p4:
	s_add_i32 s57, 0, 0x18000
	s_add_i32 s58, 0, 0x1c000
	v_add_u32_e32 v140, s57, v184
	v_add_u32_e32 v174, s58, v184
	ds_read_b128 v[128:131], v140
	ds_read_b128 v[132:135], v140 offset:1024
	ds_read_b128 v[136:139], v140 offset:2048
	ds_read_b128 v[140:143], v140 offset:3072
	ds_read_b128 v[162:165], v174
	ds_read_b128 v[166:169], v174 offset:1024
	ds_read_b128 v[170:173], v174 offset:2048
	ds_read_b128 v[174:177], v174 offset:3072
	s_add_u32 s40, s40, 0x80000
	s_addc_u32 s41, s41, 0
	s_mov_b32 m0, s44
	v_lshl_add_u64 v[226:227], s[40:41], 0, v[150:151]
	ds_read_b128 v[178:181], v188 offset:32768
	ds_read_b128 v[192:195], v188 offset:33792
	ds_read_b128 v[196:199], v188 offset:34816
	ds_read_b128 v[200:203], v188 offset:35840
	ds_read_b128 v[204:207], v188 offset:36864
	ds_read_b128 v[208:211], v188 offset:37888
	ds_read_b128 v[212:215], v188 offset:38912
	ds_read_b128 v[216:219], v188 offset:39936
	global_load_lds_dwordx4 v[226:227], off
	v_lshl_add_u64 v[226:227], s[40:41], 0, v[146:147]
	s_mov_b32 m0, s45
	s_nop 0
	global_load_lds_dwordx4 v[226:227], off
	s_waitcnt vmcnt(8)
	s_waitcnt lgkmcnt(0)
	s_waitcnt lgkmcnt(0)
	s_setprio 1
	s_barrier
	v_mfma_f32_16x16x32_bf16 v[124:127], v[128:131], v[178:181], v[124:127]
	v_mfma_f32_16x16x32_bf16 v[120:123], v[136:139], v[178:181], v[120:123]
	v_mfma_f32_16x16x32_bf16 v[108:111], v[128:131], v[196:199], v[108:111]
	v_mfma_f32_16x16x32_bf16 v[104:107], v[136:139], v[196:199], v[104:107]
	v_mfma_f32_16x16x32_bf16 v[92:95], v[128:131], v[204:207], v[92:95]
	v_mfma_f32_16x16x32_bf16 v[88:91], v[136:139], v[204:207], v[88:91]
	v_mfma_f32_16x16x32_bf16 v[76:79], v[128:131], v[212:215], v[76:79]
	v_mfma_f32_16x16x32_bf16 v[72:75], v[136:139], v[212:215], v[72:75]
	v_mfma_f32_16x16x32_bf16 v[124:127], v[132:135], v[192:195], v[124:127]
	v_mfma_f32_16x16x32_bf16 v[120:123], v[140:143], v[192:195], v[120:123]
	v_mfma_f32_16x16x32_bf16 v[108:111], v[132:135], v[200:203], v[108:111]
	v_mfma_f32_16x16x32_bf16 v[104:107], v[140:143], v[200:203], v[104:107]
	v_mfma_f32_16x16x32_bf16 v[92:95], v[132:135], v[208:211], v[92:95]
	v_mfma_f32_16x16x32_bf16 v[88:91], v[140:143], v[208:211], v[88:91]
	v_mfma_f32_16x16x32_bf16 v[76:79], v[132:135], v[216:219], v[76:79]
	v_mfma_f32_16x16x32_bf16 v[72:75], v[140:143], v[216:219], v[72:75]
	s_setprio 0
	s_setprio 1
	v_mfma_f32_16x16x32_bf16 v[116:119], v[162:165], v[178:181], v[116:119]
	v_mfma_f32_16x16x32_bf16 v[112:115], v[170:173], v[178:181], v[112:115]
	v_mfma_f32_16x16x32_bf16 v[100:103], v[162:165], v[196:199], v[100:103]
	v_mfma_f32_16x16x32_bf16 v[96:99], v[170:173], v[196:199], v[96:99]
	v_mfma_f32_16x16x32_bf16 v[84:87], v[162:165], v[204:207], v[84:87]
	v_mfma_f32_16x16x32_bf16 v[80:83], v[170:173], v[204:207], v[80:83]
	v_mfma_f32_16x16x32_bf16 v[68:71], v[162:165], v[212:215], v[68:71]
	v_mfma_f32_16x16x32_bf16 v[64:67], v[170:173], v[212:215], v[64:67]
	v_mfma_f32_16x16x32_bf16 v[116:119], v[166:169], v[192:195], v[116:119]
	v_mfma_f32_16x16x32_bf16 v[112:115], v[174:177], v[192:195], v[112:115]
	v_mfma_f32_16x16x32_bf16 v[100:103], v[166:169], v[200:203], v[100:103]
	v_mfma_f32_16x16x32_bf16 v[96:99], v[174:177], v[200:203], v[96:99]
	v_mfma_f32_16x16x32_bf16 v[84:87], v[166:169], v[208:211], v[84:87]
	v_mfma_f32_16x16x32_bf16 v[80:83], v[174:177], v[208:211], v[80:83]
	v_mfma_f32_16x16x32_bf16 v[68:71], v[166:169], v[216:219], v[68:71]
	v_mfma_f32_16x16x32_bf16 v[64:67], v[174:177], v[216:219], v[64:67]
	s_barrier
	s_setprio 0
	ds_read_b128 v[178:181], v188 offset:49152
	ds_read_b128 v[192:195], v188 offset:50176
	ds_read_b128 v[196:199], v188 offset:51200
	ds_read_b128 v[200:203], v188 offset:52224
	ds_read_b128 v[204:207], v188 offset:53248
	ds_read_b128 v[208:211], v188 offset:54272
	ds_read_b128 v[212:215], v188 offset:55296
	ds_read_b128 v[216:219], v188 offset:56320
	s_add_i32 s40, s57, s35
	s_mov_b32 m0, s40
	v_lshl_add_u64 v[182:183], v[182:183], 0, s[14:15]
	global_load_lds_dwordx4 v[182:183], off
	s_add_i32 m0, s40, 0x2000
	s_add_u32 s38, s38, 0x80080
	v_lshl_add_u64 v[182:183], v[220:221], 0, s[14:15]
	s_addc_u32 s39, s39, 0
	s_add_i32 s40, s58, s35
	global_load_lds_dwordx4 v[182:183], off
	v_lshl_add_u64 v[182:183], s[38:39], 0, v[148:149]
	s_mov_b32 m0, s40
	s_nop 0
	global_load_lds_dwordx4 v[182:183], off
	v_lshl_add_u64 v[182:183], s[38:39], 0, v[144:145]
	s_add_i32 m0, s40, 0x2000
	s_nop 0
	global_load_lds_dwordx4 v[182:183], off
	v_lshl_add_u64 v[182:183], v[222:223], 0, s[14:15]
	s_mov_b32 m0, s49
	s_nop 0
	global_load_lds_dwordx4 v[182:183], off
	v_lshl_add_u64 v[182:183], v[224:225], 0, s[14:15]
	s_mov_b32 m0, s50
	s_nop 0
	global_load_lds_dwordx4 v[182:183], off
	s_waitcnt vmcnt(8)
	s_waitcnt lgkmcnt(0)
	s_waitcnt lgkmcnt(0)
	s_setprio 1
	s_barrier
	v_mfma_f32_16x16x32_bf16 v[60:63], v[128:131], v[178:181], v[60:63]
	v_mfma_f32_16x16x32_bf16 v[56:59], v[136:139], v[178:181], v[56:59]
	v_mfma_f32_16x16x32_bf16 v[44:47], v[128:131], v[196:199], v[44:47]
	v_mfma_f32_16x16x32_bf16 v[40:43], v[136:139], v[196:199], v[40:43]
	v_mfma_f32_16x16x32_bf16 v[28:31], v[128:131], v[204:207], v[28:31]
	v_mfma_f32_16x16x32_bf16 v[24:27], v[136:139], v[204:207], v[24:27]
	v_mfma_f32_16x16x32_bf16 v[12:15], v[128:131], v[212:215], v[12:15]
	v_mfma_f32_16x16x32_bf16 v[8:11], v[136:139], v[212:215], v[8:11]
	v_mfma_f32_16x16x32_bf16 v[60:63], v[132:135], v[192:195], v[60:63]
	v_mfma_f32_16x16x32_bf16 v[56:59], v[140:143], v[192:195], v[56:59]
	v_mfma_f32_16x16x32_bf16 v[44:47], v[132:135], v[200:203], v[44:47]
	v_mfma_f32_16x16x32_bf16 v[40:43], v[140:143], v[200:203], v[40:43]
	v_mfma_f32_16x16x32_bf16 v[28:31], v[132:135], v[208:211], v[28:31]
	v_mfma_f32_16x16x32_bf16 v[24:27], v[140:143], v[208:211], v[24:27]
	v_mfma_f32_16x16x32_bf16 v[12:15], v[132:135], v[216:219], v[12:15]
	v_mfma_f32_16x16x32_bf16 v[8:11], v[140:143], v[216:219], v[8:11]
	s_setprio 0
	s_setprio 1
	v_mfma_f32_16x16x32_bf16 v[52:55], v[162:165], v[178:181], v[52:55]
	v_mfma_f32_16x16x32_bf16 v[48:51], v[170:173], v[178:181], v[48:51]
	v_mfma_f32_16x16x32_bf16 v[36:39], v[162:165], v[196:199], v[36:39]
	v_mfma_f32_16x16x32_bf16 v[32:35], v[170:173], v[196:199], v[32:35]
	s_add_i32 s56, s56, 2
	v_mfma_f32_16x16x32_bf16 v[20:23], v[162:165], v[204:207], v[20:23]
	s_add_u32 s6, s6, 0x100
	v_mfma_f32_16x16x32_bf16 v[16:19], v[170:173], v[204:207], v[16:19]
	s_addc_u32 s7, s7, 0
	v_mfma_f32_16x16x32_bf16 v[4:7], v[162:165], v[212:215], v[4:7]
	s_add_u32 s5, s5, 0x100
	v_mfma_f32_16x16x32_bf16 v[0:3], v[170:173], v[212:215], v[0:3]
	s_addc_u32 s25, s25, 0
	v_mfma_f32_16x16x32_bf16 v[52:55], v[166:169], v[192:195], v[52:55]
	s_cmp_gt_u32 s56, 29
	v_mfma_f32_16x16x32_bf16 v[48:51], v[174:177], v[192:195], v[48:51]
	v_mfma_f32_16x16x32_bf16 v[36:39], v[166:169], v[200:203], v[36:39]
	v_mfma_f32_16x16x32_bf16 v[32:35], v[174:177], v[200:203], v[32:35]
	v_mfma_f32_16x16x32_bf16 v[20:23], v[166:169], v[208:211], v[20:23]
	v_mfma_f32_16x16x32_bf16 v[16:19], v[174:177], v[208:211], v[16:19]
	v_mfma_f32_16x16x32_bf16 v[4:7], v[166:169], v[216:219], v[4:7]
	v_mfma_f32_16x16x32_bf16 v[0:3], v[174:177], v[216:219], v[0:3]
	s_barrier
	s_setprio 0
	s_cbranch_scc0 .LBB0_672
	s_and_b64 vcc, exec, s[18:19]
	s_cbranch_vccz .LBB0_675
	s_barrier
